# GEMM epilogue stores write-through (sc1); MIX1 GLU input loads prefetched at chunk start
# speedup vs baseline: 1.0246x; 1.0075x over previous
.LBB0_394:
	s_or_b64 exec, exec, s[26:27]
	s_lshl_b32 s25, s38, 6
	s_sub_i32 s25, s25, 30
	s_and_b32 s0, s38, 0x7f
	s_cmp_eq_u32 s0, 0
	s_cselect_b32 s0, 30, 0
	v_and_b32_e32 v108, 31, v164
	v_lshlrev_b32_e32 v108, 4, v108
	v_mov_b32_e32 v109, 0
	s_add_u32 s26, s44, 0x1200
	s_addc_u32 s27, s45, 0
	v_lshl_add_u64 v[108:109], s[26:27], 0, v[108:109]
	v_mov_b32_e32 v110, v164
	v_ashrrev_i32_e32 v111, 5, v110
	v_cmp_gt_u32_e32 vcc, 0xbc0, v110
	v_cmp_le_i32_e64 s[100:101], s0, v111
	s_and_b64 vcc, vcc, s[100:101]
	s_and_saveexec_b64 s[100:101], vcc
	v_add_u32_e32 v111, s25, v111
	v_mad_i64_i32 v[112:113], vcc, v111, s76, v[108:109]
	global_load_dwordx4 v[60:63], v[112:113], off
	global_load_dwordx4 v[64:67], v[112:113], off offset:512
	s_mov_b64 exec, s[100:101]
	v_add_u32_e32 v110, 0x200, v164
	v_ashrrev_i32_e32 v111, 5, v110
	v_cmp_gt_u32_e32 vcc, 0xbc0, v110
	v_cmp_le_i32_e64 s[100:101], s0, v111
	s_and_b64 vcc, vcc, s[100:101]
	s_and_saveexec_b64 s[100:101], vcc
	v_add_u32_e32 v111, s25, v111
	v_mad_i64_i32 v[112:113], vcc, v111, s76, v[108:109]
	global_load_dwordx4 v[68:71], v[112:113], off
	global_load_dwordx4 v[72:75], v[112:113], off offset:512
	s_mov_b64 exec, s[100:101]
	v_add_u32_e32 v110, 0x400, v164
	v_ashrrev_i32_e32 v111, 5, v110
	v_cmp_gt_u32_e32 vcc, 0xbc0, v110
	v_cmp_le_i32_e64 s[100:101], s0, v111
	s_and_b64 vcc, vcc, s[100:101]
	s_and_saveexec_b64 s[100:101], vcc
	v_add_u32_e32 v111, s25, v111
	v_mad_i64_i32 v[112:113], vcc, v111, s76, v[108:109]
	global_load_dwordx4 v[76:79], v[112:113], off
	global_load_dwordx4 v[80:83], v[112:113], off offset:512
	s_mov_b64 exec, s[100:101]
	v_add_u32_e32 v110, 0x600, v164
	v_ashrrev_i32_e32 v111, 5, v110
	v_cmp_gt_u32_e32 vcc, 0xbc0, v110
	v_cmp_le_i32_e64 s[100:101], s0, v111
	s_and_b64 vcc, vcc, s[100:101]
	s_and_saveexec_b64 s[100:101], vcc
	v_add_u32_e32 v111, s25, v111
	v_mad_i64_i32 v[112:113], vcc, v111, s76, v[108:109]
	global_load_dwordx4 v[84:87], v[112:113], off
	global_load_dwordx4 v[88:91], v[112:113], off offset:512
	s_mov_b64 exec, s[100:101]
	v_add_u32_e32 v110, 0x800, v164
	v_ashrrev_i32_e32 v111, 5, v110
	v_cmp_gt_u32_e32 vcc, 0xbc0, v110
	v_cmp_le_i32_e64 s[100:101], s0, v111
	s_and_b64 vcc, vcc, s[100:101]
	s_and_saveexec_b64 s[100:101], vcc
	v_add_u32_e32 v111, s25, v111
	v_mad_i64_i32 v[112:113], vcc, v111, s76, v[108:109]
	global_load_dwordx4 v[92:95], v[112:113], off
	global_load_dwordx4 v[96:99], v[112:113], off offset:512
	s_mov_b64 exec, s[100:101]
	v_add_u32_e32 v110, 0xa00, v164
	v_ashrrev_i32_e32 v111, 5, v110
	v_cmp_gt_u32_e32 vcc, 0xbc0, v110
	v_cmp_le_i32_e64 s[100:101], s0, v111
	s_and_b64 vcc, vcc, s[100:101]
	s_and_saveexec_b64 s[100:101], vcc
	v_add_u32_e32 v111, s25, v111
	v_mad_i64_i32 v[112:113], vcc, v111, s76, v[108:109]
	global_load_dwordx4 v[100:103], v[112:113], off
	global_load_dwordx4 v[104:107], v[112:113], off offset:512
	s_mov_b64 exec, s[100:101]
	s_and_b32 s25, s38, 0x7f
	s_cmp_eq_u32 s25, 0
	s_cselect_b64 s[26:27], -1, 0
	s_cmp_lg_u32 s25, 0
	s_movk_i32 s0, 0x180
	s_cselect_b64 s[36:37], -1, 0
	v_cmp_gt_i32_e32 vcc, s0, v37
	s_waitcnt lgkmcnt(0)
	s_barrier
	s_and_saveexec_b64 s[28:29], vcc
	s_cbranch_execz .LBB0_416
	s_add_u32 s34, s34, s22
	s_addc_u32 s35, s35, s23
	v_lshlrev_b32_e32 v10, 1, v37
	s_add_u32 s30, s30, s18
	v_ashrrev_i32_e32 v11, 31, v10
	s_addc_u32 s31, s31, s19
	v_lshlrev_b64 v[8:9], 2, v[10:11]
	v_lshl_add_u64 v[0:1], s[30:31], 0, v[8:9]
	v_add_co_u32_e32 v2, vcc, s1, v0
	v_lshl_add_u64 v[8:9], s[34:35], 0, v[8:9]
	s_nop 0
	v_addc_co_u32_e32 v3, vcc, 0, v1, vcc
	v_add_co_u32_e32 v4, vcc, 0x2000, v0
	s_nop 1
	v_addc_co_u32_e32 v5, vcc, 0, v1, vcc
	v_add_co_u32_e32 v6, vcc, 0x3000, v0
	s_nop 1
	v_addc_co_u32_e32 v7, vcc, 0, v1, vcc
	flat_load_dwordx2 v[0:1], v[0:1]
	s_nop 0
	flat_load_dwordx2 v[2:3], v[2:3]
	s_nop 0
	flat_load_dwordx2 v[4:5], v[4:5]
	s_nop 0
	flat_load_dwordx2 v[6:7], v[6:7]
	s_andn2_b64 vcc, exec, s[36:37]
	flat_load_dwordx2 v[8:9], v[8:9]
	s_cbranch_vccnz .LBB0_397
	s_mul_i32 s30, s16, 0x1600
	s_mul_hi_i32 s25, s16, 0x1600
	s_add_u32 s30, s44, s30
	s_addc_u32 s31, s45, s25
	v_lshl_add_u64 v[12:13], v[10:11], 1, s[30:31]
	v_add_co_u32_e32 v14, vcc, 0xffffd000, v12
	s_nop 1
	v_addc_co_u32_e32 v15, vcc, -1, v13, vcc
	global_load_dword v16, v[14:15], off offset:-2048
	v_add_co_u32_e32 v14, vcc, 0xffffe000, v12
	s_nop 1
	v_addc_co_u32_e32 v15, vcc, -1, v13, vcc
	global_load_dword v14, v[14:15], off offset:-512
	s_nop 0
	global_load_dword v15, v[12:13], off offset:-3072
	s_waitcnt vmcnt(0)
	v_lshlrev_b32_e32 v12, 16, v16
	v_and_b32_e32 v13, 0xffff0000, v16
	v_lshlrev_b32_e32 v16, 16, v14
	v_and_b32_e32 v17, 0xffff0000, v14
	v_lshlrev_b32_e32 v14, 16, v15
	v_and_b32_e32 v15, 0xffff0000, v15
	s_branch .LBB0_398

.LBB0_417:
	v_subrev_u32_e32 v39, 64, v38
	ds_read_b128 v[40:43], v39
	ds_read_b128 v[44:47], v38
	v_lshl_add_u64 v[52:53], v[34:35], 0, s[28:29]
	s_mov_b32 s17, 0x7601000
	v_add_co_u32_e32 v54, vcc, s17, v52
	s_waitcnt lgkmcnt(1)
	v_mfma_f32_16x16x32_bf16 v[48:51], v[40:43], v[0:3], 0
	v_addc_co_u32_e32 v55, vcc, 0, v53, vcc
	s_mov_b32 s17, 0x7603000
	s_waitcnt lgkmcnt(0)
	v_mfma_f32_16x16x32_bf16 v[48:51], v[44:47], v[4:7], v[48:51]
	s_add_u32 s28, s28, 32
	s_addc_u32 s29, s29, 0
	v_add_u32_e32 v38, 0x900, v38
	s_cmpk_lg_i32 s28, 0x100
	s_nop 3
	v_cvt_pk_bf16_f32 v48, v48, v49
	v_cvt_pk_bf16_f32 v49, v50, v51
	global_store_dwordx2 v[54:55], v[48:49], off offset:-4096
	v_mfma_f32_16x16x32_bf16 v[48:51], v[40:43], v[8:11], 0
	v_mfma_f32_16x16x32_bf16 v[48:51], v[44:47], v[12:15], v[48:51]
	s_nop 7
	v_cvt_pk_bf16_f32 v48, v48, v49
	v_cvt_pk_bf16_f32 v49, v50, v51
	global_store_dwordx2 v[54:55], v[48:49], off
	v_mfma_f32_16x16x32_bf16 v[48:51], v[40:43], v[16:19], 0
	v_mfma_f32_16x16x32_bf16 v[40:43], v[40:43], v[24:27], 0
	v_mfma_f32_16x16x32_bf16 v[48:51], v[44:47], v[20:23], v[48:51]
	v_mfma_f32_16x16x32_bf16 v[40:43], v[44:47], v[28:31], v[40:43]
	s_nop 6
	v_cvt_pk_bf16_f32 v48, v48, v49
	v_cvt_pk_bf16_f32 v49, v50, v51
	v_add_co_u32_e32 v50, vcc, s17, v52
	v_cvt_pk_bf16_f32 v40, v40, v41
	s_nop 0
	v_addc_co_u32_e32 v51, vcc, 0, v53, vcc
	v_cvt_pk_bf16_f32 v41, v42, v43
	global_store_dwordx2 v[50:51], v[48:49], off offset:-4096
	global_store_dwordx2 v[50:51], v[40:41], off
	s_cbranch_scc1 .LBB0_417
	v_and_b32_e32 v0, 31, v37
	s_movk_i32 s17, 0xbc0
	s_sub_i32 s16, s16, 30
	v_lshlrev_b32_e32 v5, 3, v0
	v_lshl_add_u32 v4, v0, 4, 0
	v_cmp_gt_i32_e32 vcc, s17, v37
	s_waitcnt vmcnt(0)
	s_barrier
	s_and_saveexec_b64 s[28:29], vcc
	s_cbranch_execz .LBB0_422
	v_ashrrev_i32_e32 v6, 5, v37
	v_cmp_lt_i32_e32 vcc, 29, v6
	s_xor_b64 s[30:31], s[26:27], -1
	s_or_b64 s[34:35], s[30:31], vcc
	v_mov_b32_e32 v0, 0
	v_mov_b32_e32 v1, 0
	v_mov_b32_e32 v2, 0
	v_mov_b32_e32 v3, 0
	s_and_saveexec_b64 s[30:31], s[34:35]
	s_cbranch_execz .LBB0_421
	v_add_u32_e32 v2, s16, v6
	v_mov_b64_e32 v[0:1], s[44:45]
	v_mad_i64_i32 v[0:1], s[34:35], v2, s76, v[0:1]
	v_lshlrev_b32_e32 v162, 1, v5
	v_lshl_add_u64 v[0:1], v[0:1], 0, v[162:163]
	s_mov_b64 s[34:35], 0x1200
	v_lshl_add_u64 v[8:9], v[0:1], 0, s[34:35]
	v_add_co_u32_e32 v0, vcc, 0x1000, v0
	s_nop 1
	v_addc_co_u32_e32 v1, vcc, 0, v1, vcc
	v_mov_b32_e32 v0, v60
	v_mov_b32_e32 v1, v61
	v_mov_b32_e32 v2, v62
	v_mov_b32_e32 v3, v63
	v_mov_b32_e32 v8, v64
	v_mov_b32_e32 v9, v65
	v_mov_b32_e32 v10, v66
	v_mov_b32_e32 v11, v67
	v_lshlrev_b32_e32 v14, 16, v0
	v_lshlrev_b32_e32 v7, 16, v8
	v_mul_f32_e32 v7, 0xbfb8aa3b, v7
	v_exp_f32_e32 v7, v7
	v_and_b32_e32 v15, 0xffff0000, v0
	v_add_f32_e32 v7, 1.0, v7
	v_rcp_f32_e32 v12, v7
	v_and_b32_e32 v7, 0xffff0000, v8
	v_mul_f32_e32 v7, 0xbfb8aa3b, v7
	v_exp_f32_e32 v7, v7
	s_nop 0
	v_add_f32_e32 v7, 1.0, v7
	v_rcp_f32_e32 v13, v7
	v_lshlrev_b32_e32 v7, 16, v9
	v_mul_f32_e32 v7, 0xbfb8aa3b, v7
	v_exp_f32_e32 v7, v7
	v_pk_mul_f32 v[12:13], v[12:13], v[14:15]
	v_add_f32_e32 v7, 1.0, v7
	v_rcp_f32_e32 v8, v7
	v_and_b32_e32 v7, 0xffff0000, v9
	v_mul_f32_e32 v7, 0xbfb8aa3b, v7
	v_exp_f32_e32 v7, v7
	v_cvt_pk_bf16_f32 v0, v12, v13
	v_lshlrev_b32_e32 v12, 16, v1
	v_and_b32_e32 v13, 0xffff0000, v1
	v_add_f32_e32 v7, 1.0, v7
	v_rcp_f32_e32 v9, v7
	v_lshlrev_b32_e32 v7, 16, v10
	v_mul_f32_e32 v7, 0xbfb8aa3b, v7
	v_exp_f32_e32 v7, v7
	v_pk_mul_f32 v[8:9], v[8:9], v[12:13]
	v_lshlrev_b32_e32 v12, 16, v2
	v_cvt_pk_bf16_f32 v1, v8, v9
	v_add_f32_e32 v7, 1.0, v7
	v_rcp_f32_e32 v8, v7
	v_and_b32_e32 v7, 0xffff0000, v10
	v_mul_f32_e32 v7, 0xbfb8aa3b, v7
	v_exp_f32_e32 v7, v7
	v_and_b32_e32 v13, 0xffff0000, v2
	v_lshlrev_b32_e32 v10, 16, v3
	v_add_f32_e32 v7, 1.0, v7
	v_rcp_f32_e32 v9, v7
	v_lshlrev_b32_e32 v7, 16, v11
	v_mul_f32_e32 v7, 0xbfb8aa3b, v7
	v_exp_f32_e32 v7, v7
	v_pk_mul_f32 v[8:9], v[8:9], v[12:13]
	v_add_f32_e32 v7, 1.0, v7
	v_cvt_pk_bf16_f32 v2, v8, v9
	v_rcp_f32_e32 v8, v7
	v_and_b32_e32 v7, 0xffff0000, v11
	v_mul_f32_e32 v7, 0xbfb8aa3b, v7
	v_exp_f32_e32 v7, v7
	v_and_b32_e32 v11, 0xffff0000, v3
	v_add_f32_e32 v7, 1.0, v7
	v_rcp_f32_e32 v9, v7
	s_nop 0
	v_pk_mul_f32 v[8:9], v[8:9], v[10:11]
	s_nop 0
	v_cvt_pk_bf16_f32 v3, v8, v9

.LBB0_422:
	s_or_b64 exec, exec, s[28:29]
	s_movk_i32 s17, 0x9c0
	v_cmp_gt_i32_e32 vcc, s17, v37
	s_and_saveexec_b64 s[28:29], vcc
	s_cbranch_execz .LBB0_426
	v_add_u32_e32 v0, 0x200, v37
	v_ashrrev_i32_e32 v6, 5, v0
	v_cmp_lt_i32_e32 vcc, 29, v6
	s_xor_b64 s[30:31], s[26:27], -1
	s_or_b64 s[34:35], s[30:31], vcc
	v_mov_b32_e32 v0, 0
	v_mov_b32_e32 v1, 0
	v_mov_b32_e32 v2, 0
	v_mov_b32_e32 v3, 0
	s_and_saveexec_b64 s[30:31], s[34:35]
	s_cbranch_execz .LBB0_425
	v_add_u32_e32 v2, s16, v6
	v_mov_b64_e32 v[0:1], s[44:45]
	v_mad_i64_i32 v[0:1], s[34:35], v2, s76, v[0:1]
	v_lshlrev_b32_e32 v162, 1, v5
	v_lshl_add_u64 v[0:1], v[0:1], 0, v[162:163]
	s_mov_b64 s[34:35], 0x1200
	v_lshl_add_u64 v[8:9], v[0:1], 0, s[34:35]
	v_add_co_u32_e32 v0, vcc, 0x1000, v0
	s_nop 1
	v_addc_co_u32_e32 v1, vcc, 0, v1, vcc
	v_mov_b32_e32 v0, v68
	v_mov_b32_e32 v1, v69
	v_mov_b32_e32 v2, v70
	v_mov_b32_e32 v3, v71
	v_mov_b32_e32 v8, v72
	v_mov_b32_e32 v9, v73
	v_mov_b32_e32 v10, v74
	v_mov_b32_e32 v11, v75
	v_lshlrev_b32_e32 v14, 16, v0
	v_lshlrev_b32_e32 v7, 16, v8
	v_mul_f32_e32 v7, 0xbfb8aa3b, v7
	v_exp_f32_e32 v7, v7
	v_and_b32_e32 v15, 0xffff0000, v0
	v_add_f32_e32 v7, 1.0, v7
	v_rcp_f32_e32 v12, v7
	v_and_b32_e32 v7, 0xffff0000, v8
	v_mul_f32_e32 v7, 0xbfb8aa3b, v7
	v_exp_f32_e32 v7, v7
	s_nop 0
	v_add_f32_e32 v7, 1.0, v7
	v_rcp_f32_e32 v13, v7
	v_lshlrev_b32_e32 v7, 16, v9
	v_mul_f32_e32 v7, 0xbfb8aa3b, v7
	v_exp_f32_e32 v7, v7
	v_pk_mul_f32 v[12:13], v[12:13], v[14:15]
	v_add_f32_e32 v7, 1.0, v7
	v_rcp_f32_e32 v8, v7
	v_and_b32_e32 v7, 0xffff0000, v9
	v_mul_f32_e32 v7, 0xbfb8aa3b, v7
	v_exp_f32_e32 v7, v7
	v_cvt_pk_bf16_f32 v0, v12, v13
	v_lshlrev_b32_e32 v12, 16, v1
	v_and_b32_e32 v13, 0xffff0000, v1
	v_add_f32_e32 v7, 1.0, v7
	v_rcp_f32_e32 v9, v7
	v_lshlrev_b32_e32 v7, 16, v10
	v_mul_f32_e32 v7, 0xbfb8aa3b, v7
	v_exp_f32_e32 v7, v7
	v_pk_mul_f32 v[8:9], v[8:9], v[12:13]
	v_lshlrev_b32_e32 v12, 16, v2
	v_cvt_pk_bf16_f32 v1, v8, v9
	v_add_f32_e32 v7, 1.0, v7
	v_rcp_f32_e32 v8, v7
	v_and_b32_e32 v7, 0xffff0000, v10
	v_mul_f32_e32 v7, 0xbfb8aa3b, v7
	v_exp_f32_e32 v7, v7
	v_and_b32_e32 v13, 0xffff0000, v2
	v_lshlrev_b32_e32 v10, 16, v3
	v_add_f32_e32 v7, 1.0, v7
	v_rcp_f32_e32 v9, v7
	v_lshlrev_b32_e32 v7, 16, v11
	v_mul_f32_e32 v7, 0xbfb8aa3b, v7
	v_exp_f32_e32 v7, v7
	v_pk_mul_f32 v[8:9], v[8:9], v[12:13]
	v_add_f32_e32 v7, 1.0, v7
	v_cvt_pk_bf16_f32 v2, v8, v9
	v_rcp_f32_e32 v8, v7
	v_and_b32_e32 v7, 0xffff0000, v11
	v_mul_f32_e32 v7, 0xbfb8aa3b, v7
	v_exp_f32_e32 v7, v7
	v_and_b32_e32 v11, 0xffff0000, v3
	v_add_f32_e32 v7, 1.0, v7
	v_rcp_f32_e32 v9, v7
	s_nop 0
	v_pk_mul_f32 v[8:9], v[8:9], v[10:11]
	s_nop 0
	v_cvt_pk_bf16_f32 v3, v8, v9

.LBB0_426:
	s_or_b64 exec, exec, s[28:29]
	s_movk_i32 s17, 0x7c0
	v_cmp_gt_i32_e32 vcc, s17, v37
	s_and_saveexec_b64 s[28:29], vcc
	s_cbranch_execz .LBB0_430
	v_add_u32_e32 v0, 0x400, v37
	v_ashrrev_i32_e32 v6, 5, v0
	v_cmp_lt_i32_e32 vcc, 29, v6
	s_xor_b64 s[30:31], s[26:27], -1
	s_or_b64 s[34:35], s[30:31], vcc
	v_mov_b32_e32 v0, 0
	v_mov_b32_e32 v1, 0
	v_mov_b32_e32 v2, 0
	v_mov_b32_e32 v3, 0
	s_and_saveexec_b64 s[30:31], s[34:35]
	s_cbranch_execz .LBB0_429
	v_add_u32_e32 v2, s16, v6
	v_mov_b64_e32 v[0:1], s[44:45]
	v_mad_i64_i32 v[0:1], s[34:35], v2, s76, v[0:1]
	v_lshlrev_b32_e32 v162, 1, v5
	v_lshl_add_u64 v[0:1], v[0:1], 0, v[162:163]
	s_mov_b64 s[34:35], 0x1200
	v_lshl_add_u64 v[8:9], v[0:1], 0, s[34:35]
	v_add_co_u32_e32 v0, vcc, 0x1000, v0
	s_nop 1
	v_addc_co_u32_e32 v1, vcc, 0, v1, vcc
	v_mov_b32_e32 v0, v76
	v_mov_b32_e32 v1, v77
	v_mov_b32_e32 v2, v78
	v_mov_b32_e32 v3, v79
	v_mov_b32_e32 v8, v80
	v_mov_b32_e32 v9, v81
	v_mov_b32_e32 v10, v82
	v_mov_b32_e32 v11, v83
	v_lshlrev_b32_e32 v14, 16, v0
	v_lshlrev_b32_e32 v7, 16, v8
	v_mul_f32_e32 v7, 0xbfb8aa3b, v7
	v_exp_f32_e32 v7, v7
	v_and_b32_e32 v15, 0xffff0000, v0
	v_add_f32_e32 v7, 1.0, v7
	v_rcp_f32_e32 v12, v7
	v_and_b32_e32 v7, 0xffff0000, v8
	v_mul_f32_e32 v7, 0xbfb8aa3b, v7
	v_exp_f32_e32 v7, v7
	s_nop 0
	v_add_f32_e32 v7, 1.0, v7
	v_rcp_f32_e32 v13, v7
	v_lshlrev_b32_e32 v7, 16, v9
	v_mul_f32_e32 v7, 0xbfb8aa3b, v7
	v_exp_f32_e32 v7, v7
	v_pk_mul_f32 v[12:13], v[12:13], v[14:15]
	v_add_f32_e32 v7, 1.0, v7
	v_rcp_f32_e32 v8, v7
	v_and_b32_e32 v7, 0xffff0000, v9
	v_mul_f32_e32 v7, 0xbfb8aa3b, v7
	v_exp_f32_e32 v7, v7
	v_cvt_pk_bf16_f32 v0, v12, v13
	v_lshlrev_b32_e32 v12, 16, v1
	v_and_b32_e32 v13, 0xffff0000, v1
	v_add_f32_e32 v7, 1.0, v7
	v_rcp_f32_e32 v9, v7
	v_lshlrev_b32_e32 v7, 16, v10
	v_mul_f32_e32 v7, 0xbfb8aa3b, v7
	v_exp_f32_e32 v7, v7
	v_pk_mul_f32 v[8:9], v[8:9], v[12:13]
	v_lshlrev_b32_e32 v12, 16, v2
	v_cvt_pk_bf16_f32 v1, v8, v9
	v_add_f32_e32 v7, 1.0, v7
	v_rcp_f32_e32 v8, v7
	v_and_b32_e32 v7, 0xffff0000, v10
	v_mul_f32_e32 v7, 0xbfb8aa3b, v7
	v_exp_f32_e32 v7, v7
	v_and_b32_e32 v13, 0xffff0000, v2
	v_lshlrev_b32_e32 v10, 16, v3
	v_add_f32_e32 v7, 1.0, v7
	v_rcp_f32_e32 v9, v7
	v_lshlrev_b32_e32 v7, 16, v11
	v_mul_f32_e32 v7, 0xbfb8aa3b, v7
	v_exp_f32_e32 v7, v7
	v_pk_mul_f32 v[8:9], v[8:9], v[12:13]
	v_add_f32_e32 v7, 1.0, v7
	v_cvt_pk_bf16_f32 v2, v8, v9
	v_rcp_f32_e32 v8, v7
	v_and_b32_e32 v7, 0xffff0000, v11
	v_mul_f32_e32 v7, 0xbfb8aa3b, v7
	v_exp_f32_e32 v7, v7
	v_and_b32_e32 v11, 0xffff0000, v3
	v_add_f32_e32 v7, 1.0, v7
	v_rcp_f32_e32 v9, v7
	s_nop 0
	v_pk_mul_f32 v[8:9], v[8:9], v[10:11]
	s_nop 0
	v_cvt_pk_bf16_f32 v3, v8, v9

.LBB0_430:
	s_or_b64 exec, exec, s[28:29]
	s_movk_i32 s17, 0x5c0
	v_cmp_gt_i32_e32 vcc, s17, v37
	s_and_saveexec_b64 s[28:29], vcc
	s_cbranch_execz .LBB0_434
	v_add_u32_e32 v0, 0x600, v37
	v_ashrrev_i32_e32 v6, 5, v0
	v_cmp_lt_i32_e32 vcc, 29, v6
	s_xor_b64 s[30:31], s[26:27], -1
	s_or_b64 s[34:35], s[30:31], vcc
	v_mov_b32_e32 v0, 0
	v_mov_b32_e32 v1, 0
	v_mov_b32_e32 v2, 0
	v_mov_b32_e32 v3, 0
	s_and_saveexec_b64 s[30:31], s[34:35]
	s_cbranch_execz .LBB0_433
	v_add_u32_e32 v2, s16, v6
	v_mov_b64_e32 v[0:1], s[44:45]
	v_mad_i64_i32 v[0:1], s[34:35], v2, s76, v[0:1]
	v_lshlrev_b32_e32 v162, 1, v5
	v_lshl_add_u64 v[0:1], v[0:1], 0, v[162:163]
	s_mov_b64 s[34:35], 0x1200
	v_lshl_add_u64 v[8:9], v[0:1], 0, s[34:35]
	v_add_co_u32_e32 v0, vcc, 0x1000, v0
	s_nop 1
	v_addc_co_u32_e32 v1, vcc, 0, v1, vcc
	v_mov_b32_e32 v0, v84
	v_mov_b32_e32 v1, v85
	v_mov_b32_e32 v2, v86
	v_mov_b32_e32 v3, v87
	v_mov_b32_e32 v8, v88
	v_mov_b32_e32 v9, v89
	v_mov_b32_e32 v10, v90
	v_mov_b32_e32 v11, v91
	v_lshlrev_b32_e32 v14, 16, v0
	v_lshlrev_b32_e32 v7, 16, v8
	v_mul_f32_e32 v7, 0xbfb8aa3b, v7
	v_exp_f32_e32 v7, v7
	v_and_b32_e32 v15, 0xffff0000, v0
	v_add_f32_e32 v7, 1.0, v7
	v_rcp_f32_e32 v12, v7
	v_and_b32_e32 v7, 0xffff0000, v8
	v_mul_f32_e32 v7, 0xbfb8aa3b, v7
	v_exp_f32_e32 v7, v7
	s_nop 0
	v_add_f32_e32 v7, 1.0, v7
	v_rcp_f32_e32 v13, v7
	v_lshlrev_b32_e32 v7, 16, v9
	v_mul_f32_e32 v7, 0xbfb8aa3b, v7
	v_exp_f32_e32 v7, v7
	v_pk_mul_f32 v[12:13], v[12:13], v[14:15]
	v_add_f32_e32 v7, 1.0, v7
	v_rcp_f32_e32 v8, v7
	v_and_b32_e32 v7, 0xffff0000, v9
	v_mul_f32_e32 v7, 0xbfb8aa3b, v7
	v_exp_f32_e32 v7, v7
	v_cvt_pk_bf16_f32 v0, v12, v13
	v_lshlrev_b32_e32 v12, 16, v1
	v_and_b32_e32 v13, 0xffff0000, v1
	v_add_f32_e32 v7, 1.0, v7
	v_rcp_f32_e32 v9, v7
	v_lshlrev_b32_e32 v7, 16, v10
	v_mul_f32_e32 v7, 0xbfb8aa3b, v7
	v_exp_f32_e32 v7, v7
	v_pk_mul_f32 v[8:9], v[8:9], v[12:13]
	v_lshlrev_b32_e32 v12, 16, v2
	v_cvt_pk_bf16_f32 v1, v8, v9
	v_add_f32_e32 v7, 1.0, v7
	v_rcp_f32_e32 v8, v7
	v_and_b32_e32 v7, 0xffff0000, v10
	v_mul_f32_e32 v7, 0xbfb8aa3b, v7
	v_exp_f32_e32 v7, v7
	v_and_b32_e32 v13, 0xffff0000, v2
	v_lshlrev_b32_e32 v10, 16, v3
	v_add_f32_e32 v7, 1.0, v7
	v_rcp_f32_e32 v9, v7
	v_lshlrev_b32_e32 v7, 16, v11
	v_mul_f32_e32 v7, 0xbfb8aa3b, v7
	v_exp_f32_e32 v7, v7
	v_pk_mul_f32 v[8:9], v[8:9], v[12:13]
	v_add_f32_e32 v7, 1.0, v7
	v_cvt_pk_bf16_f32 v2, v8, v9
	v_rcp_f32_e32 v8, v7
	v_and_b32_e32 v7, 0xffff0000, v11
	v_mul_f32_e32 v7, 0xbfb8aa3b, v7
	v_exp_f32_e32 v7, v7
	v_and_b32_e32 v11, 0xffff0000, v3
	v_add_f32_e32 v7, 1.0, v7
	v_rcp_f32_e32 v9, v7
	s_nop 0
	v_pk_mul_f32 v[8:9], v[8:9], v[10:11]
	s_nop 0
	v_cvt_pk_bf16_f32 v3, v8, v9

.LBB0_434:
	s_or_b64 exec, exec, s[28:29]
	s_movk_i32 s17, 0x3c0
	v_cmp_gt_i32_e32 vcc, s17, v37
	s_and_saveexec_b64 s[28:29], vcc
	s_cbranch_execz .LBB0_438
	v_add_u32_e32 v0, 0x800, v37
	v_ashrrev_i32_e32 v6, 5, v0
	v_cmp_lt_i32_e32 vcc, 29, v6
	s_xor_b64 s[30:31], s[26:27], -1
	s_or_b64 s[34:35], s[30:31], vcc
	v_mov_b32_e32 v0, 0
	v_mov_b32_e32 v1, 0
	v_mov_b32_e32 v2, 0
	v_mov_b32_e32 v3, 0
	s_and_saveexec_b64 s[30:31], s[34:35]
	s_cbranch_execz .LBB0_437
	v_add_u32_e32 v2, s16, v6
	v_mov_b64_e32 v[0:1], s[44:45]
	v_mad_i64_i32 v[0:1], s[34:35], v2, s76, v[0:1]
	v_lshlrev_b32_e32 v162, 1, v5
	v_lshl_add_u64 v[0:1], v[0:1], 0, v[162:163]
	s_mov_b64 s[34:35], 0x1200
	v_lshl_add_u64 v[8:9], v[0:1], 0, s[34:35]
	v_add_co_u32_e32 v0, vcc, 0x1000, v0
	s_nop 1
	v_addc_co_u32_e32 v1, vcc, 0, v1, vcc
	v_mov_b32_e32 v0, v92
	v_mov_b32_e32 v1, v93
	v_mov_b32_e32 v2, v94
	v_mov_b32_e32 v3, v95
	v_mov_b32_e32 v8, v96
	v_mov_b32_e32 v9, v97
	v_mov_b32_e32 v10, v98
	v_mov_b32_e32 v11, v99
	v_lshlrev_b32_e32 v14, 16, v0
	v_lshlrev_b32_e32 v7, 16, v8
	v_mul_f32_e32 v7, 0xbfb8aa3b, v7
	v_exp_f32_e32 v7, v7
	v_and_b32_e32 v15, 0xffff0000, v0
	v_add_f32_e32 v7, 1.0, v7
	v_rcp_f32_e32 v12, v7
	v_and_b32_e32 v7, 0xffff0000, v8
	v_mul_f32_e32 v7, 0xbfb8aa3b, v7
	v_exp_f32_e32 v7, v7
	s_nop 0
	v_add_f32_e32 v7, 1.0, v7
	v_rcp_f32_e32 v13, v7
	v_lshlrev_b32_e32 v7, 16, v9
	v_mul_f32_e32 v7, 0xbfb8aa3b, v7
	v_exp_f32_e32 v7, v7
	v_pk_mul_f32 v[12:13], v[12:13], v[14:15]
	v_add_f32_e32 v7, 1.0, v7
	v_rcp_f32_e32 v8, v7
	v_and_b32_e32 v7, 0xffff0000, v9
	v_mul_f32_e32 v7, 0xbfb8aa3b, v7
	v_exp_f32_e32 v7, v7
	v_cvt_pk_bf16_f32 v0, v12, v13
	v_lshlrev_b32_e32 v12, 16, v1
	v_and_b32_e32 v13, 0xffff0000, v1
	v_add_f32_e32 v7, 1.0, v7
	v_rcp_f32_e32 v9, v7
	v_lshlrev_b32_e32 v7, 16, v10
	v_mul_f32_e32 v7, 0xbfb8aa3b, v7
	v_exp_f32_e32 v7, v7
	v_pk_mul_f32 v[8:9], v[8:9], v[12:13]
	v_lshlrev_b32_e32 v12, 16, v2
	v_cvt_pk_bf16_f32 v1, v8, v9
	v_add_f32_e32 v7, 1.0, v7
	v_rcp_f32_e32 v8, v7
	v_and_b32_e32 v7, 0xffff0000, v10
	v_mul_f32_e32 v7, 0xbfb8aa3b, v7
	v_exp_f32_e32 v7, v7
	v_and_b32_e32 v13, 0xffff0000, v2
	v_lshlrev_b32_e32 v10, 16, v3
	v_add_f32_e32 v7, 1.0, v7
	v_rcp_f32_e32 v9, v7
	v_lshlrev_b32_e32 v7, 16, v11
	v_mul_f32_e32 v7, 0xbfb8aa3b, v7
	v_exp_f32_e32 v7, v7
	v_pk_mul_f32 v[8:9], v[8:9], v[12:13]
	v_add_f32_e32 v7, 1.0, v7
	v_cvt_pk_bf16_f32 v2, v8, v9
	v_rcp_f32_e32 v8, v7
	v_and_b32_e32 v7, 0xffff0000, v11
	v_mul_f32_e32 v7, 0xbfb8aa3b, v7
	v_exp_f32_e32 v7, v7
	v_and_b32_e32 v11, 0xffff0000, v3
	v_add_f32_e32 v7, 1.0, v7
	v_rcp_f32_e32 v9, v7
	s_nop 0
	v_pk_mul_f32 v[8:9], v[8:9], v[10:11]
	s_nop 0
	v_cvt_pk_bf16_f32 v3, v8, v9

.LBB0_438:
	s_or_b64 exec, exec, s[28:29]
	s_movk_i32 s17, 0x1c0
	v_cmp_gt_i32_e32 vcc, s17, v37
	s_and_saveexec_b64 s[28:29], vcc
	s_cbranch_execz .LBB0_442
	v_add_u32_e32 v0, 0xa00, v37
	v_ashrrev_i32_e32 v6, 5, v0
	v_cmp_lt_i32_e32 vcc, 29, v6
	s_xor_b64 s[26:27], s[26:27], -1
	s_or_b64 s[30:31], s[26:27], vcc
	v_mov_b32_e32 v0, 0
	v_mov_b32_e32 v1, 0
	v_mov_b32_e32 v2, 0
	v_mov_b32_e32 v3, 0
	s_and_saveexec_b64 s[26:27], s[30:31]
	s_cbranch_execz .LBB0_441
	v_add_u32_e32 v2, s16, v6
	v_mov_b64_e32 v[0:1], s[44:45]
	v_mad_i64_i32 v[0:1], s[16:17], v2, s76, v[0:1]
	v_lshlrev_b32_e32 v162, 1, v5
	v_lshl_add_u64 v[0:1], v[0:1], 0, v[162:163]
	s_mov_b64 s[16:17], 0x1200
	v_lshl_add_u64 v[8:9], v[0:1], 0, s[16:17]
	v_add_co_u32_e32 v0, vcc, 0x1000, v0
	s_nop 1
	v_addc_co_u32_e32 v1, vcc, 0, v1, vcc
	v_mov_b32_e32 v0, v100
	v_mov_b32_e32 v1, v101
	v_mov_b32_e32 v2, v102
	v_mov_b32_e32 v3, v103
	v_mov_b32_e32 v8, v104
	v_mov_b32_e32 v9, v105
	v_mov_b32_e32 v10, v106
	v_mov_b32_e32 v11, v107
	v_lshlrev_b32_e32 v14, 16, v0
	v_lshlrev_b32_e32 v5, 16, v8
	v_mul_f32_e32 v5, 0xbfb8aa3b, v5
	v_exp_f32_e32 v5, v5
	v_and_b32_e32 v15, 0xffff0000, v0
	v_add_f32_e32 v5, 1.0, v5
	v_rcp_f32_e32 v12, v5
	v_and_b32_e32 v5, 0xffff0000, v8
	v_mul_f32_e32 v5, 0xbfb8aa3b, v5
	v_exp_f32_e32 v5, v5
	s_nop 0
	v_add_f32_e32 v5, 1.0, v5
	v_rcp_f32_e32 v13, v5
	v_lshlrev_b32_e32 v5, 16, v9
	v_mul_f32_e32 v5, 0xbfb8aa3b, v5
	v_exp_f32_e32 v5, v5
	v_pk_mul_f32 v[12:13], v[12:13], v[14:15]
	v_add_f32_e32 v5, 1.0, v5
	v_rcp_f32_e32 v8, v5
	v_and_b32_e32 v5, 0xffff0000, v9
	v_mul_f32_e32 v5, 0xbfb8aa3b, v5
	v_exp_f32_e32 v5, v5
	v_cvt_pk_bf16_f32 v0, v12, v13
	v_lshlrev_b32_e32 v12, 16, v1
	v_and_b32_e32 v13, 0xffff0000, v1
	v_add_f32_e32 v5, 1.0, v5
	v_rcp_f32_e32 v9, v5
	v_lshlrev_b32_e32 v5, 16, v10
	v_mul_f32_e32 v5, 0xbfb8aa3b, v5
	v_exp_f32_e32 v5, v5
	v_pk_mul_f32 v[8:9], v[8:9], v[12:13]
	v_lshlrev_b32_e32 v12, 16, v2
	v_cvt_pk_bf16_f32 v1, v8, v9
	v_add_f32_e32 v5, 1.0, v5
	v_rcp_f32_e32 v8, v5
	v_and_b32_e32 v5, 0xffff0000, v10
	v_mul_f32_e32 v5, 0xbfb8aa3b, v5
	v_exp_f32_e32 v5, v5
	v_and_b32_e32 v13, 0xffff0000, v2
	v_lshlrev_b32_e32 v10, 16, v3
	v_add_f32_e32 v5, 1.0, v5
	v_rcp_f32_e32 v9, v5
	v_lshlrev_b32_e32 v5, 16, v11
	v_mul_f32_e32 v5, 0xbfb8aa3b, v5
	v_exp_f32_e32 v5, v5
	v_pk_mul_f32 v[8:9], v[8:9], v[12:13]
	v_add_f32_e32 v5, 1.0, v5
	v_cvt_pk_bf16_f32 v2, v8, v9
	v_rcp_f32_e32 v8, v5
	v_and_b32_e32 v5, 0xffff0000, v11
	v_mul_f32_e32 v5, 0xbfb8aa3b, v5
	v_exp_f32_e32 v5, v5
	v_and_b32_e32 v11, 0xffff0000, v3
	v_add_f32_e32 v5, 1.0, v5
	v_rcp_f32_e32 v9, v5
	s_nop 0
	v_pk_mul_f32 v[8:9], v[8:9], v[10:11]
	s_nop 0
	v_cvt_pk_bf16_f32 v3, v8, v9

.LBB0_493:
	s_cmp_lg_u32 s51, 1
	s_cbranch_scc0 .LBB0_495
	s_lshl_b32 s36, s98, 10
	s_add_i32 s36, s36, 0
	s_add_i32 s36, s36, 0x20000
	v_lshl_add_u32 v142, v155, 2, s36
	ds_read_b32 v143, v142
	v_pk_mul_f32 v[166:167], v[124:125], v[116:117]
	v_pk_mul_f32 v[160:161], v[126:127], v[118:119]
	v_pk_mul_f32 v[168:169], v[120:121], v[112:113]
	v_lshl_or_b32 v144, s13, 7, v156
	s_waitcnt lgkmcnt(0)
	v_mul_f32_e32 v162, 0xbfb8aa3b, v143
	v_pk_mul_f32 v[158:159], v[124:125], v[162:163] op_sel_hi:[1,0]
	v_mul_f32_e32 v142, v143, v143
	v_exp_f32_e32 v158, v158
	v_exp_f32_e32 v159, v159
	v_lshl_add_u32 v146, s95, 8, v148
	v_ashrrev_i32_e32 v145, 31, v144
	v_lshlrev_b64 v[144:145], 1, v[144:145]
	v_pk_add_f32 v[158:159], v[158:159], 1.0 op_sel_hi:[1,0]
	s_movk_i32 s0, 0xdf
	v_rcp_f32_e32 v158, v158
	v_rcp_f32_e32 v159, v159
	v_pk_mul_f32 v[170:171], v[104:105], v[96:97]
	v_or_b32_e32 v147, 16, v146
	v_add_u32_e32 v165, 0xb0, v146
	v_pk_mul_f32 v[158:159], v[142:143], v[158:159] op_sel_hi:[0,1]
	v_pk_mul_f32 v[158:159], v[166:167], v[158:159]
	v_pk_mul_f32 v[166:167], v[126:127], v[162:163] op_sel_hi:[1,0]
	v_cvt_pk_bf16_f32 v158, v158, v159
	s_nop 0
	v_exp_f32_e32 v166, v166
	v_exp_f32_e32 v167, v167
	s_nop 0
	v_pk_add_f32 v[166:167], v[166:167], 1.0 op_sel_hi:[1,0]
	s_nop 0
	v_rcp_f32_e32 v166, v166
	v_rcp_f32_e32 v167, v167
	s_nop 0
	v_pk_mul_f32 v[166:167], v[142:143], v[166:167] op_sel_hi:[0,1]
	v_pk_mul_f32 v[160:161], v[160:161], v[166:167]
	v_pk_mul_f32 v[166:167], v[122:123], v[114:115]
	v_cvt_pk_bf16_f32 v159, v160, v161
	v_pk_mul_f32 v[160:161], v[120:121], v[162:163] op_sel_hi:[1,0]
	s_nop 0
	v_exp_f32_e32 v160, v160
	v_exp_f32_e32 v161, v161
	s_nop 0
	v_pk_add_f32 v[160:161], v[160:161], 1.0 op_sel_hi:[1,0]
	s_nop 0
	v_rcp_f32_e32 v160, v160
	v_rcp_f32_e32 v161, v161
	s_nop 0
	v_pk_mul_f32 v[160:161], v[142:143], v[160:161] op_sel_hi:[0,1]
	v_pk_mul_f32 v[160:161], v[168:169], v[160:161]
	v_pk_mul_f32 v[168:169], v[122:123], v[162:163] op_sel_hi:[1,0]
	v_cvt_pk_bf16_f32 v160, v160, v161
	s_nop 0
	v_exp_f32_e32 v168, v168
	v_exp_f32_e32 v169, v169
	s_nop 0
	v_pk_add_f32 v[168:169], v[168:169], 1.0 op_sel_hi:[1,0]
	s_nop 0
	v_rcp_f32_e32 v168, v168
	v_rcp_f32_e32 v169, v169
	s_nop 0
	v_pk_mul_f32 v[142:143], v[142:143], v[168:169] op_sel_hi:[0,1]
	v_pk_mul_f32 v[142:143], v[166:167], v[142:143]
	v_pk_mul_f32 v[168:169], v[108:109], v[100:101]
	v_cvt_pk_bf16_f32 v161, v142, v143
	v_mov_b64_e32 v[142:143], s[20:21]
	v_mad_i64_i32 v[166:167], s[38:39], v146, s76, v[142:143]
	v_lshl_add_u64 v[166:167], v[166:167], 0, v[144:145]
	global_store_dwordx4 v[166:167], v[158:161], off sc1
	s_nop 1
	v_bitop3_b32 v158, v146, s0, 16 bitop3:0xc8
	v_lshl_add_u32 v158, v158, 2, s36
	ds_read_b32 v158, v158
	v_pk_mul_f32 v[160:161], v[110:111], v[102:103]
	s_movk_i32 s0, 0xef
	s_waitcnt lgkmcnt(0)
	v_mul_f32_e32 v166, 0xbfb8aa3b, v158
	v_mul_f32_e32 v162, v158, v158
	v_pk_mul_f32 v[158:159], v[108:109], v[166:167] op_sel_hi:[1,0]
	s_nop 0
	v_exp_f32_e32 v158, v158
	v_exp_f32_e32 v159, v159
	s_nop 0
	v_pk_add_f32 v[158:159], v[158:159], 1.0 op_sel_hi:[1,0]
	s_nop 0
	v_rcp_f32_e32 v158, v158
	v_rcp_f32_e32 v159, v159
	s_nop 0
	v_pk_mul_f32 v[158:159], v[162:163], v[158:159] op_sel_hi:[0,1]
	v_pk_mul_f32 v[158:159], v[168:169], v[158:159]
	v_pk_mul_f32 v[168:169], v[110:111], v[166:167] op_sel_hi:[1,0]
	v_cvt_pk_bf16_f32 v158, v158, v159
	s_nop 0
	v_exp_f32_e32 v168, v168
	v_exp_f32_e32 v169, v169
	s_nop 0
	v_pk_add_f32 v[168:169], v[168:169], 1.0 op_sel_hi:[1,0]
	s_nop 0
	v_rcp_f32_e32 v168, v168
	v_rcp_f32_e32 v169, v169
	s_nop 0
	v_pk_mul_f32 v[168:169], v[162:163], v[168:169] op_sel_hi:[0,1]
	v_pk_mul_f32 v[160:161], v[160:161], v[168:169]
	v_pk_mul_f32 v[168:169], v[106:107], v[98:99]
	v_cvt_pk_bf16_f32 v159, v160, v161
	v_pk_mul_f32 v[160:161], v[104:105], v[166:167] op_sel_hi:[1,0]
	v_pk_mul_f32 v[166:167], v[106:107], v[166:167] op_sel_hi:[1,0]
	v_exp_f32_e32 v160, v160
	v_exp_f32_e32 v161, v161
	v_exp_f32_e32 v166, v166
	v_exp_f32_e32 v167, v167
	v_pk_add_f32 v[160:161], v[160:161], 1.0 op_sel_hi:[1,0]
	s_nop 0
	v_rcp_f32_e32 v160, v160
	v_pk_add_f32 v[166:167], v[166:167], 1.0 op_sel_hi:[1,0]
	v_rcp_f32_e32 v161, v161
	v_rcp_f32_e32 v166, v166
	v_rcp_f32_e32 v167, v167
	v_pk_mul_f32 v[160:161], v[162:163], v[160:161] op_sel_hi:[0,1]
	v_pk_mul_f32 v[160:161], v[170:171], v[160:161]
	v_pk_mul_f32 v[166:167], v[162:163], v[166:167] op_sel_hi:[0,1]
	v_pk_mul_f32 v[166:167], v[168:169], v[166:167]
	v_cvt_pk_bf16_f32 v160, v160, v161
	v_pk_mul_f32 v[168:169], v[92:93], v[84:85]
	v_cvt_pk_bf16_f32 v161, v166, v167
	v_mad_i64_i32 v[166:167], s[38:39], v147, s76, v[142:143]
	v_lshl_add_u64 v[166:167], v[166:167], 0, v[144:145]
	global_store_dwordx4 v[166:167], v[158:161], off sc1
	v_pk_mul_f32 v[170:171], v[88:89], v[80:81]
	v_or_b32_e32 v147, 32, v146
	v_bitop3_b32 v158, v146, s0, 32 bitop3:0xc8
	v_lshl_add_u32 v158, v158, 2, s36
	ds_read_b32 v158, v158
	v_pk_mul_f32 v[160:161], v[94:95], v[86:87]
	s_movk_i32 s0, 0xff
	s_waitcnt lgkmcnt(0)
	v_mul_f32_e32 v166, 0xbfb8aa3b, v158
	v_mul_f32_e32 v162, v158, v158
	v_pk_mul_f32 v[158:159], v[92:93], v[166:167] op_sel_hi:[1,0]
	s_nop 0
	v_exp_f32_e32 v158, v158
	v_exp_f32_e32 v159, v159
	s_nop 0
	v_pk_add_f32 v[158:159], v[158:159], 1.0 op_sel_hi:[1,0]
	s_nop 0
	v_rcp_f32_e32 v158, v158
	v_rcp_f32_e32 v159, v159
	s_nop 0
	v_pk_mul_f32 v[158:159], v[162:163], v[158:159] op_sel_hi:[0,1]
	v_pk_mul_f32 v[158:159], v[168:169], v[158:159]
	v_pk_mul_f32 v[168:169], v[94:95], v[166:167] op_sel_hi:[1,0]
	v_cvt_pk_bf16_f32 v158, v158, v159
	s_nop 0
	v_exp_f32_e32 v168, v168
	v_exp_f32_e32 v169, v169
	s_nop 0
	v_pk_add_f32 v[168:169], v[168:169], 1.0 op_sel_hi:[1,0]
	s_nop 0
	v_rcp_f32_e32 v168, v168
	v_rcp_f32_e32 v169, v169
	s_nop 0
	v_pk_mul_f32 v[168:169], v[162:163], v[168:169] op_sel_hi:[0,1]
	v_pk_mul_f32 v[160:161], v[160:161], v[168:169]
	v_pk_mul_f32 v[168:169], v[90:91], v[82:83]
	v_cvt_pk_bf16_f32 v159, v160, v161
	v_pk_mul_f32 v[160:161], v[88:89], v[166:167] op_sel_hi:[1,0]
	v_pk_mul_f32 v[166:167], v[90:91], v[166:167] op_sel_hi:[1,0]
	v_exp_f32_e32 v160, v160
	v_exp_f32_e32 v161, v161
	v_exp_f32_e32 v166, v166
	v_exp_f32_e32 v167, v167
	v_pk_add_f32 v[160:161], v[160:161], 1.0 op_sel_hi:[1,0]
	s_nop 0
	v_rcp_f32_e32 v160, v160
	v_pk_add_f32 v[166:167], v[166:167], 1.0 op_sel_hi:[1,0]
	v_rcp_f32_e32 v161, v161
	v_rcp_f32_e32 v166, v166
	v_rcp_f32_e32 v167, v167
	v_pk_mul_f32 v[160:161], v[162:163], v[160:161] op_sel_hi:[0,1]
	v_pk_mul_f32 v[160:161], v[170:171], v[160:161]
	v_pk_mul_f32 v[166:167], v[162:163], v[166:167] op_sel_hi:[0,1]
	v_pk_mul_f32 v[166:167], v[168:169], v[166:167]
	v_cvt_pk_bf16_f32 v160, v160, v161
	v_pk_mul_f32 v[168:169], v[76:77], v[68:69]
	v_cvt_pk_bf16_f32 v161, v166, v167
	v_mad_i64_i32 v[166:167], s[38:39], v147, s76, v[142:143]
	v_lshl_add_u64 v[166:167], v[166:167], 0, v[144:145]
	global_store_dwordx4 v[166:167], v[158:161], off sc1
	v_pk_mul_f32 v[170:171], v[72:73], v[64:65]
	v_or_b32_e32 v147, 48, v146
	v_bitop3_b32 v158, v146, s0, 48 bitop3:0xc8
	v_lshl_add_u32 v158, v158, 2, s36
	ds_read_b32 v158, v158
	v_pk_mul_f32 v[160:161], v[78:79], v[70:71]
	s_waitcnt lgkmcnt(0)
	v_mul_f32_e32 v166, 0xbfb8aa3b, v158
	v_mul_f32_e32 v162, v158, v158
	v_pk_mul_f32 v[158:159], v[76:77], v[166:167] op_sel_hi:[1,0]
	s_nop 0
	v_exp_f32_e32 v158, v158
	v_exp_f32_e32 v159, v159
	s_nop 0
	v_pk_add_f32 v[158:159], v[158:159], 1.0 op_sel_hi:[1,0]
	s_nop 0
	v_rcp_f32_e32 v158, v158
	v_rcp_f32_e32 v159, v159
	s_nop 0
	v_pk_mul_f32 v[158:159], v[162:163], v[158:159] op_sel_hi:[0,1]
	v_pk_mul_f32 v[158:159], v[168:169], v[158:159]
	v_pk_mul_f32 v[168:169], v[78:79], v[166:167] op_sel_hi:[1,0]
	v_cvt_pk_bf16_f32 v158, v158, v159
	s_nop 0
	v_exp_f32_e32 v168, v168
	v_exp_f32_e32 v169, v169
	s_nop 0
	v_pk_add_f32 v[168:169], v[168:169], 1.0 op_sel_hi:[1,0]
	s_nop 0
	v_rcp_f32_e32 v168, v168
	v_rcp_f32_e32 v169, v169
	s_nop 0
	v_pk_mul_f32 v[168:169], v[162:163], v[168:169] op_sel_hi:[0,1]
	v_pk_mul_f32 v[160:161], v[160:161], v[168:169]
	v_pk_mul_f32 v[168:169], v[74:75], v[66:67]
	v_cvt_pk_bf16_f32 v159, v160, v161
	v_pk_mul_f32 v[160:161], v[72:73], v[166:167] op_sel_hi:[1,0]
	v_pk_mul_f32 v[166:167], v[74:75], v[166:167] op_sel_hi:[1,0]
	v_exp_f32_e32 v160, v160
	v_exp_f32_e32 v161, v161
	v_exp_f32_e32 v166, v166
	v_exp_f32_e32 v167, v167
	v_pk_add_f32 v[160:161], v[160:161], 1.0 op_sel_hi:[1,0]
	s_nop 0
	v_rcp_f32_e32 v160, v160
	v_pk_add_f32 v[166:167], v[166:167], 1.0 op_sel_hi:[1,0]
	v_rcp_f32_e32 v161, v161
	v_rcp_f32_e32 v166, v166
	v_rcp_f32_e32 v167, v167
	v_pk_mul_f32 v[160:161], v[162:163], v[160:161] op_sel_hi:[0,1]
	v_pk_mul_f32 v[160:161], v[170:171], v[160:161]
	v_pk_mul_f32 v[166:167], v[162:163], v[166:167] op_sel_hi:[0,1]
	v_pk_mul_f32 v[166:167], v[168:169], v[166:167]
	v_cvt_pk_bf16_f32 v160, v160, v161
	v_pk_mul_f32 v[168:169], v[60:61], v[52:53]
	v_cvt_pk_bf16_f32 v161, v166, v167
	v_mad_i64_i32 v[166:167], s[38:39], v147, s76, v[142:143]
	v_lshl_add_u64 v[166:167], v[166:167], 0, v[144:145]
	v_add_u32_e32 v147, 0x80, v146
	global_store_dwordx4 v[166:167], v[158:161], off sc1
	v_pk_mul_f32 v[170:171], v[56:57], v[48:49]
	s_nop 0
	v_and_b32_e32 v158, 0xcf, v147
	v_lshl_add_u32 v158, v158, 2, s36
	ds_read_b32 v158, v158
	v_pk_mul_f32 v[160:161], v[62:63], v[54:55]
	s_waitcnt lgkmcnt(0)
	v_mul_f32_e32 v166, 0xbfb8aa3b, v158
	v_mul_f32_e32 v162, v158, v158
	v_pk_mul_f32 v[158:159], v[60:61], v[166:167] op_sel_hi:[1,0]
	s_nop 0
	v_exp_f32_e32 v158, v158
	v_exp_f32_e32 v159, v159
	s_nop 0
	v_pk_add_f32 v[158:159], v[158:159], 1.0 op_sel_hi:[1,0]
	s_nop 0
	v_rcp_f32_e32 v158, v158
	v_rcp_f32_e32 v159, v159
	s_nop 0
	v_pk_mul_f32 v[158:159], v[162:163], v[158:159] op_sel_hi:[0,1]
	v_pk_mul_f32 v[158:159], v[168:169], v[158:159]
	v_pk_mul_f32 v[168:169], v[62:63], v[166:167] op_sel_hi:[1,0]
	v_cvt_pk_bf16_f32 v158, v158, v159
	s_nop 0
	v_exp_f32_e32 v168, v168
	v_exp_f32_e32 v169, v169
	s_nop 0
	v_pk_add_f32 v[168:169], v[168:169], 1.0 op_sel_hi:[1,0]
	s_nop 0
	v_rcp_f32_e32 v168, v168
	v_rcp_f32_e32 v169, v169
	s_nop 0
	v_pk_mul_f32 v[168:169], v[162:163], v[168:169] op_sel_hi:[0,1]
	v_pk_mul_f32 v[160:161], v[160:161], v[168:169]
	v_pk_mul_f32 v[168:169], v[58:59], v[50:51]
	v_cvt_pk_bf16_f32 v159, v160, v161
	v_pk_mul_f32 v[160:161], v[56:57], v[166:167] op_sel_hi:[1,0]
	v_pk_mul_f32 v[166:167], v[58:59], v[166:167] op_sel_hi:[1,0]
	v_exp_f32_e32 v160, v160
	v_exp_f32_e32 v161, v161
	v_exp_f32_e32 v166, v166
	v_exp_f32_e32 v167, v167
	v_pk_add_f32 v[160:161], v[160:161], 1.0 op_sel_hi:[1,0]
	s_nop 0
	v_rcp_f32_e32 v160, v160
	v_pk_add_f32 v[166:167], v[166:167], 1.0 op_sel_hi:[1,0]
	v_rcp_f32_e32 v161, v161
	v_rcp_f32_e32 v166, v166
	v_rcp_f32_e32 v167, v167
	v_pk_mul_f32 v[160:161], v[162:163], v[160:161] op_sel_hi:[0,1]
	v_pk_mul_f32 v[160:161], v[170:171], v[160:161]
	v_pk_mul_f32 v[166:167], v[162:163], v[166:167] op_sel_hi:[0,1]
	v_pk_mul_f32 v[166:167], v[168:169], v[166:167]
	v_cvt_pk_bf16_f32 v160, v160, v161
	v_pk_mul_f32 v[168:169], v[44:45], v[36:37]
	v_cvt_pk_bf16_f32 v161, v166, v167
	v_mad_i64_i32 v[166:167], s[38:39], v147, s76, v[142:143]
	v_lshl_add_u64 v[166:167], v[166:167], 0, v[144:145]
	v_add_u32_e32 v147, 0x90, v146
	global_store_dwordx4 v[166:167], v[158:161], off sc1
	v_pk_mul_f32 v[170:171], v[40:41], v[32:33]
	s_nop 0
	v_and_b32_e32 v158, 0xdf, v147
	v_lshl_add_u32 v158, v158, 2, s36
	ds_read_b32 v158, v158
	v_pk_mul_f32 v[160:161], v[46:47], v[38:39]
	s_waitcnt lgkmcnt(0)
	v_mul_f32_e32 v166, 0xbfb8aa3b, v158
	v_mul_f32_e32 v162, v158, v158
	v_pk_mul_f32 v[158:159], v[44:45], v[166:167] op_sel_hi:[1,0]
	s_nop 0
	v_exp_f32_e32 v158, v158
	v_exp_f32_e32 v159, v159
	s_nop 0
	v_pk_add_f32 v[158:159], v[158:159], 1.0 op_sel_hi:[1,0]
	s_nop 0
	v_rcp_f32_e32 v158, v158
	v_rcp_f32_e32 v159, v159
	s_nop 0
	v_pk_mul_f32 v[158:159], v[162:163], v[158:159] op_sel_hi:[0,1]
	v_pk_mul_f32 v[158:159], v[168:169], v[158:159]
	v_pk_mul_f32 v[168:169], v[46:47], v[166:167] op_sel_hi:[1,0]
	v_cvt_pk_bf16_f32 v158, v158, v159
	s_nop 0
	v_exp_f32_e32 v168, v168
	v_exp_f32_e32 v169, v169
	s_nop 0
	v_pk_add_f32 v[168:169], v[168:169], 1.0 op_sel_hi:[1,0]
	s_nop 0
	v_rcp_f32_e32 v168, v168
	v_rcp_f32_e32 v169, v169
	s_nop 0
	v_pk_mul_f32 v[168:169], v[162:163], v[168:169] op_sel_hi:[0,1]
	v_pk_mul_f32 v[160:161], v[160:161], v[168:169]
	v_pk_mul_f32 v[168:169], v[42:43], v[34:35]
	v_cvt_pk_bf16_f32 v159, v160, v161
	v_pk_mul_f32 v[160:161], v[40:41], v[166:167] op_sel_hi:[1,0]
	v_pk_mul_f32 v[166:167], v[42:43], v[166:167] op_sel_hi:[1,0]
	v_exp_f32_e32 v160, v160
	v_exp_f32_e32 v161, v161
	v_exp_f32_e32 v166, v166
	v_exp_f32_e32 v167, v167
	v_pk_add_f32 v[160:161], v[160:161], 1.0 op_sel_hi:[1,0]
	s_nop 0
	v_rcp_f32_e32 v160, v160
	v_pk_add_f32 v[166:167], v[166:167], 1.0 op_sel_hi:[1,0]
	v_rcp_f32_e32 v161, v161
	v_rcp_f32_e32 v166, v166
	v_rcp_f32_e32 v167, v167
	v_pk_mul_f32 v[160:161], v[162:163], v[160:161] op_sel_hi:[0,1]
	v_pk_mul_f32 v[160:161], v[170:171], v[160:161]
	v_pk_mul_f32 v[166:167], v[162:163], v[166:167] op_sel_hi:[0,1]
	v_pk_mul_f32 v[166:167], v[168:169], v[166:167]
	v_cvt_pk_bf16_f32 v160, v160, v161
	v_pk_mul_f32 v[168:169], v[28:29], v[20:21]
	v_cvt_pk_bf16_f32 v161, v166, v167
	v_mad_i64_i32 v[166:167], s[38:39], v147, s76, v[142:143]
	v_lshl_add_u64 v[166:167], v[166:167], 0, v[144:145]
	v_add_u32_e32 v147, 0xa0, v146
	global_store_dwordx4 v[166:167], v[158:161], off sc1
	v_pk_mul_f32 v[170:171], v[24:25], v[16:17]
	v_and_b32_e32 v146, 0xff, v165
	v_and_b32_e32 v158, 0xef, v147
	v_lshl_add_u32 v158, v158, 2, s36
	ds_read_b32 v158, v158
	v_pk_mul_f32 v[160:161], v[30:31], v[22:23]
	v_lshl_add_u32 v146, v146, 2, s36
	s_waitcnt lgkmcnt(0)
	v_mul_f32_e32 v166, 0xbfb8aa3b, v158
	v_mul_f32_e32 v162, v158, v158
	v_pk_mul_f32 v[158:159], v[28:29], v[166:167] op_sel_hi:[1,0]
	s_nop 0
	v_exp_f32_e32 v158, v158
	v_exp_f32_e32 v159, v159
	s_nop 0
	v_pk_add_f32 v[158:159], v[158:159], 1.0 op_sel_hi:[1,0]
	s_nop 0
	v_rcp_f32_e32 v158, v158
	v_rcp_f32_e32 v159, v159
	s_nop 0
	v_pk_mul_f32 v[158:159], v[162:163], v[158:159] op_sel_hi:[0,1]
	v_pk_mul_f32 v[158:159], v[168:169], v[158:159]
	v_pk_mul_f32 v[168:169], v[30:31], v[166:167] op_sel_hi:[1,0]
	v_cvt_pk_bf16_f32 v158, v158, v159
	s_nop 0
	v_exp_f32_e32 v168, v168
	v_exp_f32_e32 v169, v169
	s_nop 0
	v_pk_add_f32 v[168:169], v[168:169], 1.0 op_sel_hi:[1,0]
	s_nop 0
	v_rcp_f32_e32 v168, v168
	v_rcp_f32_e32 v169, v169
	s_nop 0
	v_pk_mul_f32 v[168:169], v[162:163], v[168:169] op_sel_hi:[0,1]
	v_pk_mul_f32 v[160:161], v[160:161], v[168:169]
	v_pk_mul_f32 v[168:169], v[26:27], v[18:19]
	v_cvt_pk_bf16_f32 v159, v160, v161
	v_pk_mul_f32 v[160:161], v[24:25], v[166:167] op_sel_hi:[1,0]
	v_pk_mul_f32 v[166:167], v[26:27], v[166:167] op_sel_hi:[1,0]
	v_exp_f32_e32 v160, v160
	v_exp_f32_e32 v161, v161
	v_exp_f32_e32 v166, v166
	v_exp_f32_e32 v167, v167
	v_pk_add_f32 v[160:161], v[160:161], 1.0 op_sel_hi:[1,0]
	s_nop 0
	v_rcp_f32_e32 v160, v160
	v_pk_add_f32 v[166:167], v[166:167], 1.0 op_sel_hi:[1,0]
	v_rcp_f32_e32 v161, v161
	v_rcp_f32_e32 v166, v166
	v_rcp_f32_e32 v167, v167
	v_pk_mul_f32 v[160:161], v[162:163], v[160:161] op_sel_hi:[0,1]
	v_pk_mul_f32 v[160:161], v[170:171], v[160:161]
	v_pk_mul_f32 v[166:167], v[162:163], v[166:167] op_sel_hi:[0,1]
	v_pk_mul_f32 v[166:167], v[168:169], v[166:167]
	v_cvt_pk_bf16_f32 v160, v160, v161
	v_pk_mul_f32 v[168:169], v[8:9], v[0:1]
	v_cvt_pk_bf16_f32 v161, v166, v167
	v_mad_i64_i32 v[166:167], s[38:39], v147, s76, v[142:143]
	ds_read_b32 v147, v146
	v_lshl_add_u64 v[166:167], v[166:167], 0, v[144:145]
	global_store_dwordx4 v[166:167], v[158:161], off sc1
	v_pk_mul_f32 v[166:167], v[12:13], v[4:5]
	v_mad_i64_i32 v[142:143], s[36:37], v165, s76, v[142:143]
	s_waitcnt lgkmcnt(0)
	v_mul_f32_e32 v162, 0xbfb8aa3b, v147
	v_pk_mul_f32 v[158:159], v[12:13], v[162:163] op_sel_hi:[1,0]
	v_mul_f32_e32 v146, v147, v147
	v_exp_f32_e32 v158, v158
	v_exp_f32_e32 v159, v159
	v_pk_mul_f32 v[160:161], v[14:15], v[6:7]
	v_lshl_add_u64 v[142:143], v[142:143], 0, v[144:145]
	s_mov_b64 s[36:37], 0
	v_pk_add_f32 v[158:159], v[158:159], 1.0 op_sel_hi:[1,0]
	s_nop 0
	v_rcp_f32_e32 v158, v158
	v_rcp_f32_e32 v159, v159
	s_nop 0
	v_pk_mul_f32 v[158:159], v[146:147], v[158:159] op_sel_hi:[0,1]
	v_pk_mul_f32 v[158:159], v[166:167], v[158:159]
	v_pk_mul_f32 v[166:167], v[14:15], v[162:163] op_sel_hi:[1,0]
	v_cvt_pk_bf16_f32 v158, v158, v159
	s_nop 0
	v_exp_f32_e32 v166, v166
	v_exp_f32_e32 v167, v167
	s_nop 0
	v_pk_add_f32 v[166:167], v[166:167], 1.0 op_sel_hi:[1,0]
	s_nop 0
	v_rcp_f32_e32 v166, v166
	v_rcp_f32_e32 v167, v167
	s_nop 0
	v_pk_mul_f32 v[166:167], v[146:147], v[166:167] op_sel_hi:[0,1]
	v_pk_mul_f32 v[160:161], v[160:161], v[166:167]
	v_pk_mul_f32 v[166:167], v[10:11], v[2:3]
	v_cvt_pk_bf16_f32 v159, v160, v161
	v_pk_mul_f32 v[160:161], v[8:9], v[162:163] op_sel_hi:[1,0]
	s_nop 0
	v_exp_f32_e32 v160, v160
	v_exp_f32_e32 v161, v161
	s_nop 0
	v_pk_add_f32 v[160:161], v[160:161], 1.0 op_sel_hi:[1,0]
	s_nop 0
	v_rcp_f32_e32 v160, v160
	v_rcp_f32_e32 v161, v161
	s_nop 0
	v_pk_mul_f32 v[160:161], v[146:147], v[160:161] op_sel_hi:[0,1]
	v_pk_mul_f32 v[160:161], v[168:169], v[160:161]
	v_pk_mul_f32 v[168:169], v[10:11], v[162:163] op_sel_hi:[1,0]
	v_cvt_pk_bf16_f32 v160, v160, v161
	s_nop 0
	v_exp_f32_e32 v168, v168
	v_exp_f32_e32 v169, v169
	s_nop 0
	v_pk_add_f32 v[168:169], v[168:169], 1.0 op_sel_hi:[1,0]
	s_nop 0
	v_rcp_f32_e32 v168, v168
	v_rcp_f32_e32 v169, v169
	s_nop 0
	v_pk_mul_f32 v[146:147], v[146:147], v[168:169] op_sel_hi:[0,1]
	v_pk_mul_f32 v[146:147], v[166:167], v[146:147]
	s_nop 0
	v_cvt_pk_bf16_f32 v161, v146, v147
	global_store_dwordx4 v[142:143], v[158:161], off sc1
.LBB0_495:
	s_andn2_b64 vcc, exec, s[36:37]
	s_cbranch_vccnz .LBB0_513
	s_lshl_b32 s38, s95, 8
	v_add_u32_e32 v144, s38, v148
	v_ashrrev_i32_e32 v145, 31, v144
	v_lshl_or_b32 v142, s13, 8, v156
	v_lshlrev_b64 v[146:147], 11, v[144:145]
	v_ashrrev_i32_e32 v143, 31, v142
	v_lshl_add_u64 v[146:147], s[18:19], 0, v[146:147]
	v_lshl_add_u64 v[146:147], v[142:143], 1, v[146:147]
	global_load_dwordx4 v[158:161], v[146:147], off
	s_waitcnt vmcnt(0)
	v_lshlrev_b32_e32 v166, 16, v158
	v_and_b32_e32 v167, 0xffff0000, v158
	v_lshlrev_b32_e32 v158, 16, v159
	v_and_b32_e32 v159, 0xffff0000, v159
	v_pk_add_f32 v[170:171], v[126:127], v[158:159]
	v_pk_add_f32 v[158:159], v[124:125], v[166:167]
	v_lshlrev_b32_e32 v168, 16, v160
	v_and_b32_e32 v169, 0xffff0000, v160
	v_lshlrev_b32_e32 v160, 16, v161
	v_and_b32_e32 v161, 0xffff0000, v161
	v_mul_f32_e32 v162, v159, v159
	v_mul_f32_e32 v165, v171, v171
	v_pk_add_f32 v[166:167], v[122:123], v[160:161]
	v_pk_add_f32 v[160:161], v[120:121], v[168:169]
	v_fmac_f32_e32 v162, v158, v158
	v_fmac_f32_e32 v165, v170, v170
	v_add_f32_e32 v162, v162, v165
	v_mul_f32_e32 v165, v161, v161
	v_fmac_f32_e32 v165, v160, v160
	v_cvt_pk_bf16_f32 v158, v158, v159
	v_cvt_pk_bf16_f32 v159, v170, v171
	v_cvt_pk_bf16_f32 v160, v160, v161
	v_cvt_pk_bf16_f32 v161, v166, v167
	global_store_dwordx4 v[146:147], v[158:161], off sc1
	global_load_dwordx4 v[158:161], v[146:147], off offset:256
	v_mul_f32_e32 v168, v167, v167
	v_fmac_f32_e32 v168, v166, v166
	v_add_f32_e32 v165, v165, v168
	v_add_f32_e32 v162, v162, v165
	s_waitcnt vmcnt(0)
	v_lshlrev_b32_e32 v166, 16, v158
	v_and_b32_e32 v167, 0xffff0000, v158
	v_lshlrev_b32_e32 v158, 16, v159
	v_and_b32_e32 v159, 0xffff0000, v159
	v_lshlrev_b32_e32 v168, 16, v160
	v_and_b32_e32 v169, 0xffff0000, v160
	v_lshlrev_b32_e32 v160, 16, v161
	v_and_b32_e32 v161, 0xffff0000, v161
	v_pk_add_f32 v[170:171], v[118:119], v[158:159]
	v_pk_add_f32 v[158:159], v[116:117], v[166:167]
	v_pk_add_f32 v[166:167], v[114:115], v[160:161]
	v_pk_add_f32 v[160:161], v[112:113], v[168:169]
	v_mul_f32_e32 v165, v159, v159
	v_mul_f32_e32 v168, v171, v171
	v_fmac_f32_e32 v165, v158, v158
	v_fmac_f32_e32 v168, v170, v170
	v_add_f32_e32 v165, v165, v168
	v_mul_f32_e32 v168, v161, v161
	v_mul_f32_e32 v169, v167, v167
	v_fmac_f32_e32 v168, v160, v160
	v_fmac_f32_e32 v169, v166, v166
	v_add_f32_e32 v168, v168, v169
	v_add_f32_e32 v165, v165, v168
	v_add_f32_e32 v162, v162, v165
	v_cvt_pk_bf16_f32 v158, v158, v159
	v_cvt_pk_bf16_f32 v159, v170, v171
	v_cvt_pk_bf16_f32 v160, v160, v161
	v_cvt_pk_bf16_f32 v161, v166, v167
	global_store_dwordx4 v[146:147], v[158:161], off offset:256 sc1
	ds_bpermute_b32 v146, v150, v162
	s_waitcnt lgkmcnt(0)
	v_add_f32_e32 v146, v162, v146
	ds_bpermute_b32 v147, v151, v146
	s_and_saveexec_b64 s[36:37], s[40:41]
	s_cbranch_execz .LBB0_498
	s_waitcnt lgkmcnt(0)
	v_add_f32_e32 v158, v146, v147
	s_lshl_b32 s46, s13, 2
	v_lshlrev_b64 v[146:147], 6, v[144:145]
	s_ashr_i32 s47, s46, 31
	v_lshl_add_u64 v[146:147], s[14:15], 0, v[146:147]
	v_lshl_add_u64 v[146:147], s[46:47], 2, v[146:147]
	s_lshl_b32 s96, s65, 2
	v_lshl_add_u64 v[146:147], v[146:147], 0, s[96:97]
	global_store_dword v[146:147], v158, off
.LBB0_498:
	s_or_b64 exec, exec, s[36:37]
	v_add_u32_e32 v146, s38, v152
	s_waitcnt lgkmcnt(0)
	v_ashrrev_i32_e32 v147, 31, v146
	v_lshlrev_b64 v[158:159], 11, v[146:147]
	v_lshl_add_u64 v[158:159], s[18:19], 0, v[158:159]
	v_lshl_add_u64 v[166:167], v[142:143], 1, v[158:159]
	global_load_dwordx4 v[158:161], v[166:167], off
	s_waitcnt vmcnt(0)
	v_lshlrev_b32_e32 v168, 16, v158
	v_and_b32_e32 v169, 0xffff0000, v158
	v_lshlrev_b32_e32 v158, 16, v159
	v_and_b32_e32 v159, 0xffff0000, v159
	v_pk_add_f32 v[172:173], v[110:111], v[158:159]
	v_pk_add_f32 v[158:159], v[108:109], v[168:169]
	v_lshlrev_b32_e32 v170, 16, v160
	v_and_b32_e32 v171, 0xffff0000, v160
	v_lshlrev_b32_e32 v160, 16, v161
	v_and_b32_e32 v161, 0xffff0000, v161
	v_mul_f32_e32 v145, v159, v159
	v_mul_f32_e32 v162, v173, v173
	v_pk_add_f32 v[168:169], v[106:107], v[160:161]
	v_pk_add_f32 v[160:161], v[104:105], v[170:171]
	v_fmac_f32_e32 v145, v158, v158
	v_fmac_f32_e32 v162, v172, v172
	v_add_f32_e32 v145, v145, v162
	v_mul_f32_e32 v162, v161, v161
	v_fmac_f32_e32 v162, v160, v160
	v_cvt_pk_bf16_f32 v158, v158, v159
	v_cvt_pk_bf16_f32 v159, v172, v173
	v_cvt_pk_bf16_f32 v160, v160, v161
	v_cvt_pk_bf16_f32 v161, v168, v169
	global_store_dwordx4 v[166:167], v[158:161], off sc1
	global_load_dwordx4 v[158:161], v[166:167], off offset:256
	v_mul_f32_e32 v165, v169, v169
	v_fmac_f32_e32 v165, v168, v168
	v_add_f32_e32 v162, v162, v165
	v_add_f32_e32 v145, v145, v162
	s_waitcnt vmcnt(0)
	v_lshlrev_b32_e32 v168, 16, v158
	v_and_b32_e32 v169, 0xffff0000, v158
	v_lshlrev_b32_e32 v158, 16, v159
	v_and_b32_e32 v159, 0xffff0000, v159
	v_pk_add_f32 v[172:173], v[102:103], v[158:159]
	v_pk_add_f32 v[158:159], v[100:101], v[168:169]
	v_lshlrev_b32_e32 v170, 16, v160
	v_and_b32_e32 v171, 0xffff0000, v160
	v_lshlrev_b32_e32 v160, 16, v161
	v_and_b32_e32 v161, 0xffff0000, v161
	v_mul_f32_e32 v162, v159, v159
	v_mul_f32_e32 v165, v173, v173
	v_pk_add_f32 v[168:169], v[98:99], v[160:161]
	v_pk_add_f32 v[160:161], v[96:97], v[170:171]
	v_fmac_f32_e32 v162, v158, v158
	v_fmac_f32_e32 v165, v172, v172
	v_add_f32_e32 v162, v162, v165
	v_mul_f32_e32 v165, v161, v161
	v_mul_f32_e32 v170, v169, v169
	v_fmac_f32_e32 v165, v160, v160
	v_fmac_f32_e32 v170, v168, v168
	v_add_f32_e32 v165, v165, v170
	v_add_f32_e32 v162, v162, v165
	v_add_f32_e32 v145, v145, v162
	v_cvt_pk_bf16_f32 v158, v158, v159
	v_cvt_pk_bf16_f32 v159, v172, v173
	v_cvt_pk_bf16_f32 v160, v160, v161
	v_cvt_pk_bf16_f32 v161, v168, v169
	global_store_dwordx4 v[166:167], v[158:161], off offset:256 sc1
	ds_bpermute_b32 v158, v150, v145
	s_waitcnt lgkmcnt(0)
	v_add_f32_e32 v145, v145, v158
	ds_bpermute_b32 v158, v151, v145
	s_and_saveexec_b64 s[36:37], s[40:41]
	s_cbranch_execz .LBB0_500
	s_lshl_b32 s46, s13, 2
	v_lshlrev_b64 v[146:147], 6, v[146:147]
	s_ashr_i32 s47, s46, 31
	v_lshl_add_u64 v[146:147], s[14:15], 0, v[146:147]
	v_lshl_add_u64 v[146:147], s[46:47], 2, v[146:147]
	s_lshl_b32 s96, s65, 2
	s_waitcnt lgkmcnt(0)
	v_add_f32_e32 v145, v145, v158
	v_lshl_add_u64 v[146:147], v[146:147], 0, s[96:97]
	global_store_dword v[146:147], v145, off
.LBB0_500:
	s_or_b64 exec, exec, s[36:37]
	v_add_u32_e32 v146, s38, v153
	v_ashrrev_i32_e32 v147, 31, v146
	s_waitcnt lgkmcnt(0)
	v_lshlrev_b64 v[158:159], 11, v[146:147]
	v_lshl_add_u64 v[158:159], s[18:19], 0, v[158:159]
	v_lshl_add_u64 v[166:167], v[142:143], 1, v[158:159]
	global_load_dwordx4 v[158:161], v[166:167], off
	s_waitcnt vmcnt(0)
	v_lshlrev_b32_e32 v168, 16, v158
	v_and_b32_e32 v169, 0xffff0000, v158
	v_lshlrev_b32_e32 v158, 16, v159
	v_and_b32_e32 v159, 0xffff0000, v159
	v_pk_add_f32 v[172:173], v[94:95], v[158:159]
	v_pk_add_f32 v[158:159], v[92:93], v[168:169]
	v_lshlrev_b32_e32 v170, 16, v160
	v_and_b32_e32 v171, 0xffff0000, v160
	v_lshlrev_b32_e32 v160, 16, v161
	v_and_b32_e32 v161, 0xffff0000, v161
	v_mul_f32_e32 v145, v159, v159
	v_mul_f32_e32 v162, v173, v173
	v_pk_add_f32 v[168:169], v[90:91], v[160:161]
	v_pk_add_f32 v[160:161], v[88:89], v[170:171]
	v_fmac_f32_e32 v145, v158, v158
	v_fmac_f32_e32 v162, v172, v172
	v_add_f32_e32 v145, v145, v162
	v_mul_f32_e32 v162, v161, v161
	v_fmac_f32_e32 v162, v160, v160
	v_cvt_pk_bf16_f32 v158, v158, v159
	v_cvt_pk_bf16_f32 v159, v172, v173
	v_cvt_pk_bf16_f32 v160, v160, v161
	v_cvt_pk_bf16_f32 v161, v168, v169
	global_store_dwordx4 v[166:167], v[158:161], off sc1
	global_load_dwordx4 v[158:161], v[166:167], off offset:256
	v_mul_f32_e32 v165, v169, v169
	v_fmac_f32_e32 v165, v168, v168
	v_add_f32_e32 v162, v162, v165
	v_add_f32_e32 v145, v145, v162
	s_waitcnt vmcnt(0)
	v_lshlrev_b32_e32 v168, 16, v158
	v_and_b32_e32 v169, 0xffff0000, v158
	v_lshlrev_b32_e32 v158, 16, v159
	v_and_b32_e32 v159, 0xffff0000, v159
	v_pk_add_f32 v[172:173], v[86:87], v[158:159]
	v_pk_add_f32 v[158:159], v[84:85], v[168:169]
	v_lshlrev_b32_e32 v170, 16, v160
	v_and_b32_e32 v171, 0xffff0000, v160
	v_lshlrev_b32_e32 v160, 16, v161
	v_and_b32_e32 v161, 0xffff0000, v161
	v_mul_f32_e32 v162, v159, v159
	v_mul_f32_e32 v165, v173, v173
	v_pk_add_f32 v[168:169], v[82:83], v[160:161]
	v_pk_add_f32 v[160:161], v[80:81], v[170:171]
	v_fmac_f32_e32 v162, v158, v158
	v_fmac_f32_e32 v165, v172, v172
	v_add_f32_e32 v162, v162, v165
	v_mul_f32_e32 v165, v161, v161
	v_mul_f32_e32 v170, v169, v169
	v_fmac_f32_e32 v165, v160, v160
	v_fmac_f32_e32 v170, v168, v168
	v_add_f32_e32 v165, v165, v170
	v_add_f32_e32 v162, v162, v165
	v_add_f32_e32 v145, v145, v162
	v_cvt_pk_bf16_f32 v158, v158, v159
	v_cvt_pk_bf16_f32 v159, v172, v173
	v_cvt_pk_bf16_f32 v160, v160, v161
	v_cvt_pk_bf16_f32 v161, v168, v169
	global_store_dwordx4 v[166:167], v[158:161], off offset:256 sc1
	ds_bpermute_b32 v158, v150, v145
	s_waitcnt lgkmcnt(0)
	v_add_f32_e32 v145, v145, v158
	ds_bpermute_b32 v158, v151, v145
	s_and_saveexec_b64 s[36:37], s[40:41]
	s_cbranch_execz .LBB0_502
	s_lshl_b32 s46, s13, 2
	v_lshlrev_b64 v[146:147], 6, v[146:147]
	s_ashr_i32 s47, s46, 31
	v_lshl_add_u64 v[146:147], s[14:15], 0, v[146:147]
	v_lshl_add_u64 v[146:147], s[46:47], 2, v[146:147]
	s_lshl_b32 s96, s65, 2
	s_waitcnt lgkmcnt(0)
	v_add_f32_e32 v145, v145, v158
	v_lshl_add_u64 v[146:147], v[146:147], 0, s[96:97]
	global_store_dword v[146:147], v145, off
.LBB0_502:
	s_or_b64 exec, exec, s[36:37]
	v_add_u32_e32 v146, s38, v154
	v_ashrrev_i32_e32 v147, 31, v146
	s_waitcnt lgkmcnt(0)
	v_lshlrev_b64 v[158:159], 11, v[146:147]
	v_lshl_add_u64 v[158:159], s[18:19], 0, v[158:159]
	v_lshl_add_u64 v[166:167], v[142:143], 1, v[158:159]
	global_load_dwordx4 v[158:161], v[166:167], off
	s_waitcnt vmcnt(0)
	v_lshlrev_b32_e32 v168, 16, v158
	v_and_b32_e32 v169, 0xffff0000, v158
	v_lshlrev_b32_e32 v158, 16, v159
	v_and_b32_e32 v159, 0xffff0000, v159
	v_pk_add_f32 v[172:173], v[78:79], v[158:159]
	v_pk_add_f32 v[158:159], v[76:77], v[168:169]
	v_lshlrev_b32_e32 v170, 16, v160
	v_and_b32_e32 v171, 0xffff0000, v160
	v_lshlrev_b32_e32 v160, 16, v161
	v_and_b32_e32 v161, 0xffff0000, v161
	v_mul_f32_e32 v145, v159, v159
	v_mul_f32_e32 v162, v173, v173
	v_pk_add_f32 v[168:169], v[74:75], v[160:161]
	v_pk_add_f32 v[160:161], v[72:73], v[170:171]
	v_fmac_f32_e32 v145, v158, v158
	v_fmac_f32_e32 v162, v172, v172
	v_add_f32_e32 v145, v145, v162
	v_mul_f32_e32 v162, v161, v161
	v_fmac_f32_e32 v162, v160, v160
	v_cvt_pk_bf16_f32 v158, v158, v159
	v_cvt_pk_bf16_f32 v159, v172, v173
	v_cvt_pk_bf16_f32 v160, v160, v161
	v_cvt_pk_bf16_f32 v161, v168, v169
	global_store_dwordx4 v[166:167], v[158:161], off sc1
	global_load_dwordx4 v[158:161], v[166:167], off offset:256
	v_mul_f32_e32 v165, v169, v169
	v_fmac_f32_e32 v165, v168, v168
	v_add_f32_e32 v162, v162, v165
	v_add_f32_e32 v145, v145, v162
	s_waitcnt vmcnt(0)
	v_lshlrev_b32_e32 v168, 16, v158
	v_and_b32_e32 v169, 0xffff0000, v158
	v_lshlrev_b32_e32 v158, 16, v159
	v_and_b32_e32 v159, 0xffff0000, v159
	v_pk_add_f32 v[172:173], v[70:71], v[158:159]
	v_pk_add_f32 v[158:159], v[68:69], v[168:169]
	v_lshlrev_b32_e32 v170, 16, v160
	v_and_b32_e32 v171, 0xffff0000, v160
	v_lshlrev_b32_e32 v160, 16, v161
	v_and_b32_e32 v161, 0xffff0000, v161
	v_mul_f32_e32 v162, v159, v159
	v_mul_f32_e32 v165, v173, v173
	v_pk_add_f32 v[168:169], v[66:67], v[160:161]
	v_pk_add_f32 v[160:161], v[64:65], v[170:171]
	v_fmac_f32_e32 v162, v158, v158
	v_fmac_f32_e32 v165, v172, v172
	v_add_f32_e32 v162, v162, v165
	v_mul_f32_e32 v165, v161, v161
	v_mul_f32_e32 v170, v169, v169
	v_fmac_f32_e32 v165, v160, v160
	v_fmac_f32_e32 v170, v168, v168
	v_add_f32_e32 v165, v165, v170
	v_add_f32_e32 v162, v162, v165
	v_add_f32_e32 v145, v145, v162
	v_cvt_pk_bf16_f32 v158, v158, v159
	v_cvt_pk_bf16_f32 v159, v172, v173
	v_cvt_pk_bf16_f32 v160, v160, v161
	v_cvt_pk_bf16_f32 v161, v168, v169
	global_store_dwordx4 v[166:167], v[158:161], off offset:256 sc1
	ds_bpermute_b32 v158, v150, v145
	s_waitcnt lgkmcnt(0)
	v_add_f32_e32 v145, v145, v158
	ds_bpermute_b32 v158, v151, v145
	s_and_saveexec_b64 s[36:37], s[40:41]
	s_cbranch_execz .LBB0_504
	s_lshl_b32 s38, s13, 2
	v_lshlrev_b64 v[146:147], 6, v[146:147]
	s_ashr_i32 s39, s38, 31
	v_lshl_add_u64 v[146:147], s[14:15], 0, v[146:147]
	v_lshl_add_u64 v[146:147], s[38:39], 2, v[146:147]
	s_lshl_b32 s96, s65, 2
	s_waitcnt lgkmcnt(0)
	v_add_f32_e32 v145, v145, v158
	v_lshl_add_u64 v[146:147], v[146:147], 0, s[96:97]
	global_store_dword v[146:147], v145, off
.LBB0_504:
	s_or_b64 exec, exec, s[36:37]
	v_add_u32_e32 v146, 0x80, v144
	v_ashrrev_i32_e32 v147, 31, v146
	s_waitcnt lgkmcnt(0)
	v_lshlrev_b64 v[158:159], 11, v[146:147]
	v_lshl_add_u64 v[158:159], s[18:19], 0, v[158:159]
	v_lshl_add_u64 v[166:167], v[142:143], 1, v[158:159]
	global_load_dwordx4 v[158:161], v[166:167], off
	s_waitcnt vmcnt(0)
	v_lshlrev_b32_e32 v168, 16, v158
	v_and_b32_e32 v169, 0xffff0000, v158
	v_lshlrev_b32_e32 v158, 16, v159
	v_and_b32_e32 v159, 0xffff0000, v159
	v_pk_add_f32 v[172:173], v[62:63], v[158:159]
	v_pk_add_f32 v[158:159], v[60:61], v[168:169]
	v_lshlrev_b32_e32 v170, 16, v160
	v_and_b32_e32 v171, 0xffff0000, v160
	v_lshlrev_b32_e32 v160, 16, v161
	v_and_b32_e32 v161, 0xffff0000, v161
	v_mul_f32_e32 v145, v159, v159
	v_mul_f32_e32 v162, v173, v173
	v_pk_add_f32 v[168:169], v[58:59], v[160:161]
	v_pk_add_f32 v[160:161], v[56:57], v[170:171]
	v_fmac_f32_e32 v145, v158, v158
	v_fmac_f32_e32 v162, v172, v172
	v_add_f32_e32 v145, v145, v162
	v_mul_f32_e32 v162, v161, v161
	v_fmac_f32_e32 v162, v160, v160
	v_cvt_pk_bf16_f32 v158, v158, v159
	v_cvt_pk_bf16_f32 v159, v172, v173
	v_cvt_pk_bf16_f32 v160, v160, v161
	v_cvt_pk_bf16_f32 v161, v168, v169
	global_store_dwordx4 v[166:167], v[158:161], off sc1
	global_load_dwordx4 v[158:161], v[166:167], off offset:256
	v_mul_f32_e32 v165, v169, v169
	v_fmac_f32_e32 v165, v168, v168
	v_add_f32_e32 v162, v162, v165
	v_add_f32_e32 v145, v145, v162
	s_waitcnt vmcnt(0)
	v_lshlrev_b32_e32 v168, 16, v158
	v_and_b32_e32 v169, 0xffff0000, v158
	v_lshlrev_b32_e32 v158, 16, v159
	v_and_b32_e32 v159, 0xffff0000, v159
	v_pk_add_f32 v[172:173], v[54:55], v[158:159]
	v_pk_add_f32 v[158:159], v[52:53], v[168:169]
	v_lshlrev_b32_e32 v170, 16, v160
	v_and_b32_e32 v171, 0xffff0000, v160
	v_lshlrev_b32_e32 v160, 16, v161
	v_and_b32_e32 v161, 0xffff0000, v161
	v_mul_f32_e32 v162, v159, v159
	v_mul_f32_e32 v165, v173, v173
	v_pk_add_f32 v[168:169], v[50:51], v[160:161]
	v_pk_add_f32 v[160:161], v[48:49], v[170:171]
	v_fmac_f32_e32 v162, v158, v158
	v_fmac_f32_e32 v165, v172, v172
	v_add_f32_e32 v162, v162, v165
	v_mul_f32_e32 v165, v161, v161
	v_mul_f32_e32 v170, v169, v169
	v_fmac_f32_e32 v165, v160, v160
	v_fmac_f32_e32 v170, v168, v168
	v_add_f32_e32 v165, v165, v170
	v_add_f32_e32 v162, v162, v165
	v_add_f32_e32 v145, v145, v162
	v_cvt_pk_bf16_f32 v158, v158, v159
	v_cvt_pk_bf16_f32 v159, v172, v173
	v_cvt_pk_bf16_f32 v160, v160, v161
	v_cvt_pk_bf16_f32 v161, v168, v169
	global_store_dwordx4 v[166:167], v[158:161], off offset:256 sc1
	ds_bpermute_b32 v158, v150, v145
	s_waitcnt lgkmcnt(0)
	v_add_f32_e32 v145, v145, v158
	ds_bpermute_b32 v158, v151, v145
	s_and_saveexec_b64 s[36:37], s[40:41]
	s_cbranch_execz .LBB0_506
	s_lshl_b32 s38, s13, 2
	v_lshlrev_b64 v[146:147], 6, v[146:147]
	s_ashr_i32 s39, s38, 31
	v_lshl_add_u64 v[146:147], s[14:15], 0, v[146:147]
	v_lshl_add_u64 v[146:147], s[38:39], 2, v[146:147]
	s_lshl_b32 s96, s65, 2
	s_waitcnt lgkmcnt(0)
	v_add_f32_e32 v145, v145, v158
	v_lshl_add_u64 v[146:147], v[146:147], 0, s[96:97]
	global_store_dword v[146:147], v145, off
.LBB0_506:
	s_or_b64 exec, exec, s[36:37]
	v_add_u32_e32 v146, 0x90, v144
	v_ashrrev_i32_e32 v147, 31, v146
	s_waitcnt lgkmcnt(0)
	v_lshlrev_b64 v[158:159], 11, v[146:147]
	v_lshl_add_u64 v[158:159], s[18:19], 0, v[158:159]
	v_lshl_add_u64 v[166:167], v[142:143], 1, v[158:159]
	global_load_dwordx4 v[158:161], v[166:167], off
	s_waitcnt vmcnt(0)
	v_lshlrev_b32_e32 v168, 16, v158
	v_and_b32_e32 v169, 0xffff0000, v158
	v_lshlrev_b32_e32 v158, 16, v159
	v_and_b32_e32 v159, 0xffff0000, v159
	v_pk_add_f32 v[172:173], v[46:47], v[158:159]
	v_pk_add_f32 v[158:159], v[44:45], v[168:169]
	v_lshlrev_b32_e32 v170, 16, v160
	v_and_b32_e32 v171, 0xffff0000, v160
	v_lshlrev_b32_e32 v160, 16, v161
	v_and_b32_e32 v161, 0xffff0000, v161
	v_mul_f32_e32 v145, v159, v159
	v_mul_f32_e32 v162, v173, v173
	v_pk_add_f32 v[168:169], v[42:43], v[160:161]
	v_pk_add_f32 v[160:161], v[40:41], v[170:171]
	v_fmac_f32_e32 v145, v158, v158
	v_fmac_f32_e32 v162, v172, v172
	v_add_f32_e32 v145, v145, v162
	v_mul_f32_e32 v162, v161, v161
	v_fmac_f32_e32 v162, v160, v160
	v_cvt_pk_bf16_f32 v158, v158, v159
	v_cvt_pk_bf16_f32 v159, v172, v173
	v_cvt_pk_bf16_f32 v160, v160, v161
	v_cvt_pk_bf16_f32 v161, v168, v169
	global_store_dwordx4 v[166:167], v[158:161], off sc1
	global_load_dwordx4 v[158:161], v[166:167], off offset:256
	v_mul_f32_e32 v165, v169, v169
	v_fmac_f32_e32 v165, v168, v168
	v_add_f32_e32 v162, v162, v165
	v_add_f32_e32 v145, v145, v162
	s_waitcnt vmcnt(0)
	v_lshlrev_b32_e32 v168, 16, v158
	v_and_b32_e32 v169, 0xffff0000, v158
	v_lshlrev_b32_e32 v158, 16, v159
	v_and_b32_e32 v159, 0xffff0000, v159
	v_pk_add_f32 v[172:173], v[38:39], v[158:159]
	v_pk_add_f32 v[158:159], v[36:37], v[168:169]
	v_lshlrev_b32_e32 v170, 16, v160
	v_and_b32_e32 v171, 0xffff0000, v160
	v_lshlrev_b32_e32 v160, 16, v161
	v_and_b32_e32 v161, 0xffff0000, v161
	v_mul_f32_e32 v162, v159, v159
	v_mul_f32_e32 v165, v173, v173
	v_pk_add_f32 v[168:169], v[34:35], v[160:161]
	v_pk_add_f32 v[160:161], v[32:33], v[170:171]
	v_fmac_f32_e32 v162, v158, v158
	v_fmac_f32_e32 v165, v172, v172
	v_add_f32_e32 v162, v162, v165
	v_mul_f32_e32 v165, v161, v161
	v_mul_f32_e32 v170, v169, v169
	v_fmac_f32_e32 v165, v160, v160
	v_fmac_f32_e32 v170, v168, v168
	v_add_f32_e32 v165, v165, v170
	v_add_f32_e32 v162, v162, v165
	v_add_f32_e32 v145, v145, v162
	v_cvt_pk_bf16_f32 v158, v158, v159
	v_cvt_pk_bf16_f32 v159, v172, v173
	v_cvt_pk_bf16_f32 v160, v160, v161
	v_cvt_pk_bf16_f32 v161, v168, v169
	global_store_dwordx4 v[166:167], v[158:161], off offset:256 sc1
	ds_bpermute_b32 v158, v150, v145
	s_waitcnt lgkmcnt(0)
	v_add_f32_e32 v145, v145, v158
	ds_bpermute_b32 v158, v151, v145
	s_and_saveexec_b64 s[36:37], s[40:41]
	s_cbranch_execz .LBB0_508
	s_lshl_b32 s38, s13, 2
	v_lshlrev_b64 v[146:147], 6, v[146:147]
	s_ashr_i32 s39, s38, 31
	v_lshl_add_u64 v[146:147], s[14:15], 0, v[146:147]
	v_lshl_add_u64 v[146:147], s[38:39], 2, v[146:147]
	s_lshl_b32 s96, s65, 2
	s_waitcnt lgkmcnt(0)
	v_add_f32_e32 v145, v145, v158
	v_lshl_add_u64 v[146:147], v[146:147], 0, s[96:97]
	global_store_dword v[146:147], v145, off
.LBB0_508:
	s_or_b64 exec, exec, s[36:37]
	v_add_u32_e32 v146, 0xa0, v144
	v_ashrrev_i32_e32 v147, 31, v146
	s_waitcnt lgkmcnt(0)
	v_lshlrev_b64 v[158:159], 11, v[146:147]
	v_lshl_add_u64 v[158:159], s[18:19], 0, v[158:159]
	v_lshl_add_u64 v[166:167], v[142:143], 1, v[158:159]
	global_load_dwordx4 v[158:161], v[166:167], off
	s_waitcnt vmcnt(0)
	v_lshlrev_b32_e32 v168, 16, v158
	v_and_b32_e32 v169, 0xffff0000, v158
	v_lshlrev_b32_e32 v158, 16, v159
	v_and_b32_e32 v159, 0xffff0000, v159
	v_pk_add_f32 v[172:173], v[30:31], v[158:159]
	v_pk_add_f32 v[158:159], v[28:29], v[168:169]
	v_lshlrev_b32_e32 v170, 16, v160
	v_and_b32_e32 v171, 0xffff0000, v160
	v_lshlrev_b32_e32 v160, 16, v161
	v_and_b32_e32 v161, 0xffff0000, v161
	v_mul_f32_e32 v145, v159, v159
	v_mul_f32_e32 v162, v173, v173
	v_pk_add_f32 v[168:169], v[26:27], v[160:161]
	v_pk_add_f32 v[160:161], v[24:25], v[170:171]
	v_fmac_f32_e32 v145, v158, v158
	v_fmac_f32_e32 v162, v172, v172
	v_add_f32_e32 v145, v145, v162
	v_mul_f32_e32 v162, v161, v161
	v_fmac_f32_e32 v162, v160, v160
	v_cvt_pk_bf16_f32 v158, v158, v159
	v_cvt_pk_bf16_f32 v159, v172, v173
	v_cvt_pk_bf16_f32 v160, v160, v161
	v_cvt_pk_bf16_f32 v161, v168, v169
	global_store_dwordx4 v[166:167], v[158:161], off sc1
	global_load_dwordx4 v[158:161], v[166:167], off offset:256
	v_mul_f32_e32 v165, v169, v169
	v_fmac_f32_e32 v165, v168, v168
	v_add_f32_e32 v162, v162, v165
	v_add_f32_e32 v145, v145, v162
	s_waitcnt vmcnt(0)
	v_lshlrev_b32_e32 v168, 16, v158
	v_and_b32_e32 v169, 0xffff0000, v158
	v_lshlrev_b32_e32 v158, 16, v159
	v_and_b32_e32 v159, 0xffff0000, v159
	v_pk_add_f32 v[172:173], v[22:23], v[158:159]
	v_pk_add_f32 v[158:159], v[20:21], v[168:169]
	v_lshlrev_b32_e32 v170, 16, v160
	v_and_b32_e32 v171, 0xffff0000, v160
	v_lshlrev_b32_e32 v160, 16, v161
	v_and_b32_e32 v161, 0xffff0000, v161
	v_mul_f32_e32 v162, v159, v159
	v_mul_f32_e32 v165, v173, v173
	v_pk_add_f32 v[168:169], v[18:19], v[160:161]
	v_pk_add_f32 v[160:161], v[16:17], v[170:171]
	v_fmac_f32_e32 v162, v158, v158
	v_fmac_f32_e32 v165, v172, v172
	v_add_f32_e32 v162, v162, v165
	v_mul_f32_e32 v165, v161, v161
	v_mul_f32_e32 v170, v169, v169
	v_fmac_f32_e32 v165, v160, v160
	v_fmac_f32_e32 v170, v168, v168
	v_add_f32_e32 v165, v165, v170
	v_add_f32_e32 v162, v162, v165
	v_add_f32_e32 v145, v145, v162
	v_cvt_pk_bf16_f32 v158, v158, v159
	v_cvt_pk_bf16_f32 v159, v172, v173
	v_cvt_pk_bf16_f32 v160, v160, v161
	v_cvt_pk_bf16_f32 v161, v168, v169
	global_store_dwordx4 v[166:167], v[158:161], off offset:256 sc1
	ds_bpermute_b32 v158, v150, v145
	s_waitcnt lgkmcnt(0)
	v_add_f32_e32 v145, v145, v158
	ds_bpermute_b32 v158, v151, v145
	s_and_saveexec_b64 s[36:37], s[40:41]
	s_cbranch_execz .LBB0_510
	s_lshl_b32 s38, s13, 2
	v_lshlrev_b64 v[146:147], 6, v[146:147]
	s_ashr_i32 s39, s38, 31
	v_lshl_add_u64 v[146:147], s[14:15], 0, v[146:147]
	v_lshl_add_u64 v[146:147], s[38:39], 2, v[146:147]
	s_lshl_b32 s96, s65, 2
	s_waitcnt lgkmcnt(0)
	v_add_f32_e32 v145, v145, v158
	v_lshl_add_u64 v[146:147], v[146:147], 0, s[96:97]
	global_store_dword v[146:147], v145, off
.LBB0_510:
	s_or_b64 exec, exec, s[36:37]
	v_add_u32_e32 v144, 0xb0, v144
	v_ashrrev_i32_e32 v145, 31, v144
	v_lshlrev_b64 v[146:147], 11, v[144:145]
	v_lshl_add_u64 v[146:147], s[18:19], 0, v[146:147]
	v_lshl_add_u64 v[142:143], v[142:143], 1, v[146:147]
	s_waitcnt lgkmcnt(0)
	global_load_dwordx4 v[158:161], v[142:143], off
	s_waitcnt vmcnt(0)
	v_lshlrev_b32_e32 v146, 16, v158
	v_and_b32_e32 v147, 0xffff0000, v158
	v_lshlrev_b32_e32 v158, 16, v159
	v_and_b32_e32 v159, 0xffff0000, v159
	v_pk_add_f32 v[168:169], v[14:15], v[158:159]
	v_pk_add_f32 v[146:147], v[12:13], v[146:147]
	v_lshlrev_b32_e32 v166, 16, v160
	v_and_b32_e32 v167, 0xffff0000, v160
	v_lshlrev_b32_e32 v160, 16, v161
	v_and_b32_e32 v161, 0xffff0000, v161
	v_mul_f32_e32 v158, v147, v147
	v_mul_f32_e32 v159, v169, v169
	v_pk_add_f32 v[170:171], v[10:11], v[160:161]
	v_pk_add_f32 v[160:161], v[8:9], v[166:167]
	v_fmac_f32_e32 v158, v146, v146
	v_fmac_f32_e32 v159, v168, v168
	v_add_f32_e32 v158, v158, v159
	v_mul_f32_e32 v159, v161, v161
	v_mul_f32_e32 v162, v171, v171
	v_fmac_f32_e32 v159, v160, v160
	v_fmac_f32_e32 v162, v170, v170
	v_add_f32_e32 v159, v159, v162
	v_add_f32_e32 v162, v158, v159
	v_cvt_pk_bf16_f32 v158, v146, v147
	v_cvt_pk_bf16_f32 v159, v168, v169
	v_cvt_pk_bf16_f32 v160, v160, v161
	v_cvt_pk_bf16_f32 v161, v170, v171
	global_store_dwordx4 v[142:143], v[158:161], off sc1
	global_load_dwordx4 v[158:161], v[142:143], off offset:256
	s_waitcnt vmcnt(0)
	v_lshlrev_b32_e32 v146, 16, v158
	v_and_b32_e32 v147, 0xffff0000, v158
	v_lshlrev_b32_e32 v158, 16, v159
	v_and_b32_e32 v159, 0xffff0000, v159
	v_pk_add_f32 v[168:169], v[6:7], v[158:159]
	v_pk_add_f32 v[146:147], v[4:5], v[146:147]
	v_lshlrev_b32_e32 v166, 16, v160
	v_and_b32_e32 v167, 0xffff0000, v160
	v_lshlrev_b32_e32 v160, 16, v161
	v_and_b32_e32 v161, 0xffff0000, v161
	v_mul_f32_e32 v158, v147, v147
	v_mul_f32_e32 v159, v169, v169
	v_pk_add_f32 v[170:171], v[2:3], v[160:161]
	v_pk_add_f32 v[160:161], v[0:1], v[166:167]
	v_fmac_f32_e32 v158, v146, v146
	v_fmac_f32_e32 v159, v168, v168
	v_add_f32_e32 v158, v158, v159
	v_mul_f32_e32 v159, v161, v161
	v_mul_f32_e32 v165, v171, v171
	v_fmac_f32_e32 v159, v160, v160
	v_fmac_f32_e32 v165, v170, v170
	v_add_f32_e32 v159, v159, v165
	v_add_f32_e32 v158, v158, v159
	v_add_f32_e32 v162, v162, v158
	v_cvt_pk_bf16_f32 v158, v146, v147
	v_cvt_pk_bf16_f32 v159, v168, v169
	v_cvt_pk_bf16_f32 v160, v160, v161
	v_cvt_pk_bf16_f32 v161, v170, v171
	global_store_dwordx4 v[142:143], v[158:161], off offset:256 sc1
	ds_bpermute_b32 v142, v150, v162
	s_waitcnt lgkmcnt(0)
	v_add_f32_e32 v142, v162, v142
	ds_bpermute_b32 v143, v151, v142
	s_and_saveexec_b64 s[36:37], s[40:41]
	s_cbranch_execz .LBB0_512
	s_waitcnt lgkmcnt(0)
	v_add_f32_e32 v146, v142, v143
	s_lshl_b32 s38, s13, 2
	v_lshlrev_b64 v[142:143], 6, v[144:145]
	s_ashr_i32 s39, s38, 31
	v_lshl_add_u64 v[142:143], s[14:15], 0, v[142:143]
	v_lshl_add_u64 v[142:143], s[38:39], 2, v[142:143]
	s_lshl_b32 s96, s65, 2
	v_lshl_add_u64 v[142:143], v[142:143], 0, s[96:97]
	global_store_dword v[142:143], v146, off

.LBB0_514:
	s_cmp_eq_u32 s13, 0
	s_cselect_b64 vcc, -1, 0
	s_lshl_b32 s36, s98, 10
	s_add_i32 s58, s36, 0
	s_add_i32 s58, s58, 0x20000
	v_lshl_add_u32 v142, v155, 2, s58
	s_waitcnt lgkmcnt(0)
	ds_read_b32 v143, v142
	s_cmp_gt_i32 s13, 10
	v_cndmask_b32_e32 v145, 1.0, v228, vcc
	s_cselect_b64 s[36:37], -1, 0
	v_lshl_add_u32 v142, s95, 8, v148
	s_mov_b64 s[38:39], -1
	s_waitcnt lgkmcnt(0)
	v_mul_f32_e32 v144, v145, v143
	s_and_b64 vcc, exec, s[36:37]
	s_cbranch_vccz .LBB0_518
	s_and_saveexec_b64 s[38:39], s[42:43]
	s_cbranch_execz .LBB0_517
	v_ashrrev_i32_e32 v143, 31, v142
	v_lshlrev_b64 v[146:147], 5, v[142:143]
	v_lshl_add_u64 v[146:147], s[34:35], 0, v[146:147]
	v_pk_mul_f32 v[168:169], v[126:127], v[144:145] op_sel_hi:[1,0]
	v_pk_mul_f32 v[166:167], v[124:125], v[144:145] op_sel_hi:[1,0]
	v_pk_mul_f32 v[160:161], v[122:123], v[144:145] op_sel_hi:[1,0]
	v_pk_mul_f32 v[158:159], v[120:121], v[144:145] op_sel_hi:[1,0]
	global_store_dwordx4 v[146:147], v[166:169], off sc1
	global_store_dwordx4 v[146:147], v[158:161], off offset:16 sc1

.LBB0_518:
	s_andn2_b64 vcc, exec, s[38:39]
	v_lshlrev_b32_e32 v162, 1, v136
	s_cbranch_vccnz .LBB0_520
	v_mov_b64_e32 v[146:147], s[20:21]
	v_mad_i64_i32 v[146:147], s[38:39], v142, s76, v[146:147]
	s_lshl_b32 s38, s13, 8
	s_ashr_i32 s39, s38, 31
	v_lshl_add_u64 v[146:147], s[38:39], 1, v[146:147]
	s_lshl_b32 s96, s67, 1
	v_lshl_add_u64 v[146:147], v[146:147], 0, s[96:97]
	v_lshl_add_u64 v[146:147], v[146:147], 0, v[162:163]
	v_pk_mul_f32 v[126:127], v[126:127], v[144:145] op_sel_hi:[1,0]
	v_pk_mul_f32 v[124:125], v[124:125], v[144:145] op_sel_hi:[1,0]
	v_pk_mul_f32 v[158:159], v[122:123], v[144:145] op_sel_hi:[1,0]
	v_pk_mul_f32 v[122:123], v[120:121], v[144:145] op_sel_hi:[1,0]
	v_cvt_pk_bf16_f32 v120, v124, v125
	v_cvt_pk_bf16_f32 v121, v126, v127
	v_pk_mul_f32 v[118:119], v[118:119], v[144:145] op_sel_hi:[1,0]
	v_cvt_pk_bf16_f32 v122, v122, v123
	v_cvt_pk_bf16_f32 v123, v158, v159
	global_store_dwordx4 v[146:147], v[120:123], off sc1
	v_pk_mul_f32 v[116:117], v[116:117], v[144:145] op_sel_hi:[1,0]
	s_nop 0
	v_pk_mul_f32 v[120:121], v[114:115], v[144:145] op_sel_hi:[1,0]
	v_pk_mul_f32 v[114:115], v[112:113], v[144:145] op_sel_hi:[1,0]
	v_cvt_pk_bf16_f32 v112, v116, v117
	v_cvt_pk_bf16_f32 v113, v118, v119
	s_nop 0
	v_cvt_pk_bf16_f32 v114, v114, v115
	v_cvt_pk_bf16_f32 v115, v120, v121
	global_store_dwordx4 v[146:147], v[112:115], off offset:256 sc1
.LBB0_520:
	s_movk_i32 s0, 0xdf
	s_nop 0
	v_bitop3_b32 v112, v142, s0, 16 bitop3:0xc8
	v_lshl_add_u32 v112, v112, 2, s58
	ds_read_b32 v112, v112
	v_cndmask_b32_e64 v113, 0, 1, s[36:37]
	v_or_b32_e32 v114, 16, v142
	v_cmp_ne_u32_e64 s[46:47], 1, v113
	s_andn2_b64 vcc, exec, s[36:37]
	s_waitcnt lgkmcnt(0)
	v_mul_f32_e32 v112, v145, v112
	s_mov_b64 s[36:37], -1
	s_cbranch_vccnz .LBB0_524
	s_and_saveexec_b64 s[36:37], s[42:43]
	s_cbranch_execz .LBB0_523
	v_ashrrev_i32_e32 v115, 31, v114
	v_lshlrev_b64 v[116:117], 5, v[114:115]
	v_lshl_add_u64 v[124:125], s[34:35], 0, v[116:117]
	v_pk_mul_f32 v[122:123], v[110:111], v[112:113] op_sel_hi:[1,0]
	v_pk_mul_f32 v[120:121], v[108:109], v[112:113] op_sel_hi:[1,0]
	v_pk_mul_f32 v[118:119], v[106:107], v[112:113] op_sel_hi:[1,0]
	v_pk_mul_f32 v[116:117], v[104:105], v[112:113] op_sel_hi:[1,0]
	global_store_dwordx4 v[124:125], v[120:123], off sc1
	global_store_dwordx4 v[124:125], v[116:119], off offset:16 sc1

.LBB0_524:
	s_andn2_b64 vcc, exec, s[36:37]
	s_cbranch_vccnz .LBB0_526
	v_mov_b64_e32 v[116:117], s[20:21]
	v_mad_i64_i32 v[114:115], s[36:37], v114, s76, v[116:117]
	s_lshl_b32 s36, s13, 8
	s_ashr_i32 s37, s36, 31
	v_lshl_add_u64 v[114:115], s[36:37], 1, v[114:115]
	s_lshl_b32 s96, s67, 1
	v_lshl_add_u64 v[114:115], v[114:115], 0, s[96:97]
	v_lshl_add_u64 v[114:115], v[114:115], 0, v[162:163]
	v_pk_mul_f32 v[110:111], v[110:111], v[112:113] op_sel_hi:[1,0]
	v_pk_mul_f32 v[108:109], v[108:109], v[112:113] op_sel_hi:[1,0]
	v_pk_mul_f32 v[116:117], v[106:107], v[112:113] op_sel_hi:[1,0]
	v_pk_mul_f32 v[106:107], v[104:105], v[112:113] op_sel_hi:[1,0]
	v_cvt_pk_bf16_f32 v104, v108, v109
	v_cvt_pk_bf16_f32 v105, v110, v111
	v_pk_mul_f32 v[102:103], v[102:103], v[112:113] op_sel_hi:[1,0]
	v_cvt_pk_bf16_f32 v106, v106, v107
	v_cvt_pk_bf16_f32 v107, v116, v117
	global_store_dwordx4 v[114:115], v[104:107], off sc1
	v_pk_mul_f32 v[100:101], v[100:101], v[112:113] op_sel_hi:[1,0]
	s_nop 0
	v_pk_mul_f32 v[104:105], v[98:99], v[112:113] op_sel_hi:[1,0]
	v_pk_mul_f32 v[98:99], v[96:97], v[112:113] op_sel_hi:[1,0]
	v_cvt_pk_bf16_f32 v96, v100, v101
	v_cvt_pk_bf16_f32 v97, v102, v103
	s_nop 0
	v_cvt_pk_bf16_f32 v98, v98, v99
	v_cvt_pk_bf16_f32 v99, v104, v105
	global_store_dwordx4 v[114:115], v[96:99], off offset:256 sc1
.LBB0_526:
	s_movk_i32 s0, 0xef
	s_nop 0
	v_bitop3_b32 v96, v142, s0, 32 bitop3:0xc8
	v_lshl_add_u32 v96, v96, 2, s58
	ds_read_b32 v96, v96
	v_or_b32_e32 v98, 32, v142
	s_and_b64 vcc, exec, s[46:47]
	s_mov_b64 s[36:37], -1
	s_waitcnt lgkmcnt(0)
	v_mul_f32_e32 v96, v145, v96
	s_cbranch_vccnz .LBB0_530
	s_and_saveexec_b64 s[36:37], s[42:43]
	s_cbranch_execz .LBB0_529
	v_ashrrev_i32_e32 v99, 31, v98
	v_lshlrev_b64 v[100:101], 5, v[98:99]
	v_lshl_add_u64 v[108:109], s[34:35], 0, v[100:101]
	v_pk_mul_f32 v[106:107], v[94:95], v[96:97] op_sel_hi:[1,0]
	v_pk_mul_f32 v[104:105], v[92:93], v[96:97] op_sel_hi:[1,0]
	v_pk_mul_f32 v[102:103], v[90:91], v[96:97] op_sel_hi:[1,0]
	v_pk_mul_f32 v[100:101], v[88:89], v[96:97] op_sel_hi:[1,0]
	global_store_dwordx4 v[108:109], v[104:107], off sc1
	global_store_dwordx4 v[108:109], v[100:103], off offset:16 sc1

.LBB0_530:
	s_andn2_b64 vcc, exec, s[36:37]
	s_cbranch_vccnz .LBB0_532
	v_mov_b64_e32 v[100:101], s[20:21]
	v_mad_i64_i32 v[98:99], s[36:37], v98, s76, v[100:101]
	s_lshl_b32 s36, s13, 8
	s_ashr_i32 s37, s36, 31
	v_lshl_add_u64 v[98:99], s[36:37], 1, v[98:99]
	s_lshl_b32 s96, s67, 1
	v_lshl_add_u64 v[98:99], v[98:99], 0, s[96:97]
	v_lshl_add_u64 v[98:99], v[98:99], 0, v[162:163]
	v_pk_mul_f32 v[94:95], v[94:95], v[96:97] op_sel_hi:[1,0]
	v_pk_mul_f32 v[92:93], v[92:93], v[96:97] op_sel_hi:[1,0]
	v_pk_mul_f32 v[100:101], v[90:91], v[96:97] op_sel_hi:[1,0]
	v_pk_mul_f32 v[90:91], v[88:89], v[96:97] op_sel_hi:[1,0]
	v_cvt_pk_bf16_f32 v88, v92, v93
	v_cvt_pk_bf16_f32 v89, v94, v95
	v_pk_mul_f32 v[86:87], v[86:87], v[96:97] op_sel_hi:[1,0]
	v_cvt_pk_bf16_f32 v90, v90, v91
	v_cvt_pk_bf16_f32 v91, v100, v101
	global_store_dwordx4 v[98:99], v[88:91], off sc1
	v_pk_mul_f32 v[84:85], v[84:85], v[96:97] op_sel_hi:[1,0]
	s_nop 0
	v_pk_mul_f32 v[88:89], v[82:83], v[96:97] op_sel_hi:[1,0]
	v_pk_mul_f32 v[82:83], v[80:81], v[96:97] op_sel_hi:[1,0]
	v_cvt_pk_bf16_f32 v80, v84, v85
	v_cvt_pk_bf16_f32 v81, v86, v87
	s_nop 0
	v_cvt_pk_bf16_f32 v82, v82, v83
	v_cvt_pk_bf16_f32 v83, v88, v89
	global_store_dwordx4 v[98:99], v[80:83], off offset:256 sc1
.LBB0_532:
	s_movk_i32 s0, 0xff
	s_nop 0
	v_bitop3_b32 v80, v142, s0, 48 bitop3:0xc8
	v_lshl_add_u32 v80, v80, 2, s58
	ds_read_b32 v80, v80
	v_or_b32_e32 v82, 48, v142
	s_and_b64 vcc, exec, s[46:47]
	s_mov_b64 s[36:37], -1
	s_waitcnt lgkmcnt(0)
	v_mul_f32_e32 v80, v145, v80
	s_cbranch_vccnz .LBB0_536
	s_and_saveexec_b64 s[36:37], s[42:43]
	s_cbranch_execz .LBB0_535
	v_ashrrev_i32_e32 v83, 31, v82
	v_lshlrev_b64 v[84:85], 5, v[82:83]
	v_lshl_add_u64 v[92:93], s[34:35], 0, v[84:85]
	v_pk_mul_f32 v[90:91], v[78:79], v[80:81] op_sel_hi:[1,0]
	v_pk_mul_f32 v[88:89], v[76:77], v[80:81] op_sel_hi:[1,0]
	v_pk_mul_f32 v[86:87], v[74:75], v[80:81] op_sel_hi:[1,0]
	v_pk_mul_f32 v[84:85], v[72:73], v[80:81] op_sel_hi:[1,0]
	global_store_dwordx4 v[92:93], v[88:91], off sc1
	global_store_dwordx4 v[92:93], v[84:87], off offset:16 sc1

.LBB0_536:
	s_andn2_b64 vcc, exec, s[36:37]
	s_cbranch_vccnz .LBB0_538
	v_mov_b64_e32 v[84:85], s[20:21]
	v_mad_i64_i32 v[82:83], s[36:37], v82, s76, v[84:85]
	s_lshl_b32 s36, s13, 8
	s_ashr_i32 s37, s36, 31
	v_lshl_add_u64 v[82:83], s[36:37], 1, v[82:83]
	s_lshl_b32 s96, s67, 1
	v_lshl_add_u64 v[82:83], v[82:83], 0, s[96:97]
	v_lshl_add_u64 v[82:83], v[82:83], 0, v[162:163]
	v_pk_mul_f32 v[78:79], v[78:79], v[80:81] op_sel_hi:[1,0]
	v_pk_mul_f32 v[76:77], v[76:77], v[80:81] op_sel_hi:[1,0]
	v_pk_mul_f32 v[84:85], v[74:75], v[80:81] op_sel_hi:[1,0]
	v_pk_mul_f32 v[74:75], v[72:73], v[80:81] op_sel_hi:[1,0]
	v_cvt_pk_bf16_f32 v72, v76, v77
	v_cvt_pk_bf16_f32 v73, v78, v79
	v_pk_mul_f32 v[70:71], v[70:71], v[80:81] op_sel_hi:[1,0]
	v_cvt_pk_bf16_f32 v74, v74, v75
	v_cvt_pk_bf16_f32 v75, v84, v85
	global_store_dwordx4 v[82:83], v[72:75], off sc1
	v_pk_mul_f32 v[68:69], v[68:69], v[80:81] op_sel_hi:[1,0]
	s_nop 0
	v_pk_mul_f32 v[72:73], v[66:67], v[80:81] op_sel_hi:[1,0]
	v_pk_mul_f32 v[66:67], v[64:65], v[80:81] op_sel_hi:[1,0]
	v_cvt_pk_bf16_f32 v64, v68, v69
	v_cvt_pk_bf16_f32 v65, v70, v71
	s_nop 0
	v_cvt_pk_bf16_f32 v66, v66, v67
	v_cvt_pk_bf16_f32 v67, v72, v73
	global_store_dwordx4 v[82:83], v[64:67], off offset:256 sc1
.LBB0_538:
	s_nop 1
	v_add_u32_e32 v66, 0x80, v142
	v_and_b32_e32 v64, 0xcf, v66
	v_lshl_add_u32 v64, v64, 2, s58
	ds_read_b32 v64, v64
	s_and_b64 vcc, exec, s[46:47]
	s_mov_b64 s[36:37], -1
	s_waitcnt lgkmcnt(0)
	v_mul_f32_e32 v64, v145, v64
	s_cbranch_vccnz .LBB0_542
	s_and_saveexec_b64 s[36:37], s[42:43]
	s_cbranch_execz .LBB0_541
	v_ashrrev_i32_e32 v67, 31, v66
	v_lshlrev_b64 v[68:69], 5, v[66:67]
	v_lshl_add_u64 v[76:77], s[34:35], 0, v[68:69]
	v_pk_mul_f32 v[74:75], v[62:63], v[64:65] op_sel_hi:[1,0]
	v_pk_mul_f32 v[72:73], v[60:61], v[64:65] op_sel_hi:[1,0]
	v_pk_mul_f32 v[70:71], v[58:59], v[64:65] op_sel_hi:[1,0]
	v_pk_mul_f32 v[68:69], v[56:57], v[64:65] op_sel_hi:[1,0]
	global_store_dwordx4 v[76:77], v[72:75], off sc1
	global_store_dwordx4 v[76:77], v[68:71], off offset:16 sc1

.LBB0_542:
	s_andn2_b64 vcc, exec, s[36:37]
	s_cbranch_vccnz .LBB0_544
	v_mov_b64_e32 v[68:69], s[20:21]
	v_mad_i64_i32 v[66:67], s[36:37], v66, s76, v[68:69]
	s_lshl_b32 s36, s13, 8
	s_ashr_i32 s37, s36, 31
	v_lshl_add_u64 v[66:67], s[36:37], 1, v[66:67]
	s_lshl_b32 s96, s67, 1
	v_lshl_add_u64 v[66:67], v[66:67], 0, s[96:97]
	v_lshl_add_u64 v[66:67], v[66:67], 0, v[162:163]
	v_pk_mul_f32 v[62:63], v[62:63], v[64:65] op_sel_hi:[1,0]
	v_pk_mul_f32 v[60:61], v[60:61], v[64:65] op_sel_hi:[1,0]
	v_pk_mul_f32 v[68:69], v[58:59], v[64:65] op_sel_hi:[1,0]
	v_pk_mul_f32 v[58:59], v[56:57], v[64:65] op_sel_hi:[1,0]
	v_cvt_pk_bf16_f32 v56, v60, v61
	v_cvt_pk_bf16_f32 v57, v62, v63
	v_pk_mul_f32 v[54:55], v[54:55], v[64:65] op_sel_hi:[1,0]
	v_cvt_pk_bf16_f32 v58, v58, v59
	v_cvt_pk_bf16_f32 v59, v68, v69
	global_store_dwordx4 v[66:67], v[56:59], off sc1
	v_pk_mul_f32 v[52:53], v[52:53], v[64:65] op_sel_hi:[1,0]
	s_nop 0
	v_pk_mul_f32 v[56:57], v[50:51], v[64:65] op_sel_hi:[1,0]
	v_pk_mul_f32 v[50:51], v[48:49], v[64:65] op_sel_hi:[1,0]
	v_cvt_pk_bf16_f32 v48, v52, v53
	v_cvt_pk_bf16_f32 v49, v54, v55
	s_nop 0
	v_cvt_pk_bf16_f32 v50, v50, v51
	v_cvt_pk_bf16_f32 v51, v56, v57
	global_store_dwordx4 v[66:67], v[48:51], off offset:256 sc1
.LBB0_544:
	s_nop 1
	v_add_u32_e32 v50, 0x90, v142
	v_and_b32_e32 v48, 0xdf, v50
	v_lshl_add_u32 v48, v48, 2, s58
	ds_read_b32 v48, v48
	s_and_b64 vcc, exec, s[46:47]
	s_mov_b64 s[36:37], -1
	s_waitcnt lgkmcnt(0)
	v_mul_f32_e32 v48, v145, v48
	s_cbranch_vccnz .LBB0_548
	s_and_saveexec_b64 s[36:37], s[42:43]
	s_cbranch_execz .LBB0_547
	v_ashrrev_i32_e32 v51, 31, v50
	v_lshlrev_b64 v[52:53], 5, v[50:51]
	v_lshl_add_u64 v[60:61], s[34:35], 0, v[52:53]
	v_pk_mul_f32 v[58:59], v[46:47], v[48:49] op_sel_hi:[1,0]
	v_pk_mul_f32 v[56:57], v[44:45], v[48:49] op_sel_hi:[1,0]
	v_pk_mul_f32 v[54:55], v[42:43], v[48:49] op_sel_hi:[1,0]
	v_pk_mul_f32 v[52:53], v[40:41], v[48:49] op_sel_hi:[1,0]
	global_store_dwordx4 v[60:61], v[56:59], off sc1
	global_store_dwordx4 v[60:61], v[52:55], off offset:16 sc1

.LBB0_548:
	s_andn2_b64 vcc, exec, s[36:37]
	s_cbranch_vccnz .LBB0_550
	v_mov_b64_e32 v[52:53], s[20:21]
	v_mad_i64_i32 v[50:51], s[36:37], v50, s76, v[52:53]
	s_lshl_b32 s36, s13, 8
	s_ashr_i32 s37, s36, 31
	v_lshl_add_u64 v[50:51], s[36:37], 1, v[50:51]
	s_lshl_b32 s96, s67, 1
	v_lshl_add_u64 v[50:51], v[50:51], 0, s[96:97]
	v_lshl_add_u64 v[50:51], v[50:51], 0, v[162:163]
	v_pk_mul_f32 v[46:47], v[46:47], v[48:49] op_sel_hi:[1,0]
	v_pk_mul_f32 v[44:45], v[44:45], v[48:49] op_sel_hi:[1,0]
	v_pk_mul_f32 v[52:53], v[42:43], v[48:49] op_sel_hi:[1,0]
	v_pk_mul_f32 v[42:43], v[40:41], v[48:49] op_sel_hi:[1,0]
	v_cvt_pk_bf16_f32 v40, v44, v45
	v_cvt_pk_bf16_f32 v41, v46, v47
	v_pk_mul_f32 v[38:39], v[38:39], v[48:49] op_sel_hi:[1,0]
	v_cvt_pk_bf16_f32 v42, v42, v43
	v_cvt_pk_bf16_f32 v43, v52, v53
	global_store_dwordx4 v[50:51], v[40:43], off sc1
	v_pk_mul_f32 v[36:37], v[36:37], v[48:49] op_sel_hi:[1,0]
	s_nop 0
	v_pk_mul_f32 v[40:41], v[34:35], v[48:49] op_sel_hi:[1,0]
	v_pk_mul_f32 v[34:35], v[32:33], v[48:49] op_sel_hi:[1,0]
	v_cvt_pk_bf16_f32 v32, v36, v37
	v_cvt_pk_bf16_f32 v33, v38, v39
	s_nop 0
	v_cvt_pk_bf16_f32 v34, v34, v35
	v_cvt_pk_bf16_f32 v35, v40, v41
	global_store_dwordx4 v[50:51], v[32:35], off offset:256 sc1
.LBB0_550:
	s_nop 1
	v_add_u32_e32 v34, 0xa0, v142
	v_and_b32_e32 v32, 0xef, v34
	v_lshl_add_u32 v32, v32, 2, s58
	ds_read_b32 v32, v32
	s_and_b64 vcc, exec, s[46:47]
	s_mov_b64 s[36:37], -1
	s_waitcnt lgkmcnt(0)
	v_mul_f32_e32 v32, v145, v32
	s_cbranch_vccnz .LBB0_554
	s_and_saveexec_b64 s[36:37], s[42:43]
	s_cbranch_execz .LBB0_553
	v_ashrrev_i32_e32 v35, 31, v34
	v_lshlrev_b64 v[36:37], 5, v[34:35]
	v_lshl_add_u64 v[44:45], s[34:35], 0, v[36:37]
	v_pk_mul_f32 v[42:43], v[30:31], v[32:33] op_sel_hi:[1,0]
	v_pk_mul_f32 v[40:41], v[28:29], v[32:33] op_sel_hi:[1,0]
	v_pk_mul_f32 v[38:39], v[26:27], v[32:33] op_sel_hi:[1,0]
	v_pk_mul_f32 v[36:37], v[24:25], v[32:33] op_sel_hi:[1,0]
	global_store_dwordx4 v[44:45], v[40:43], off sc1
	global_store_dwordx4 v[44:45], v[36:39], off offset:16 sc1

.LBB0_554:
	s_andn2_b64 vcc, exec, s[36:37]
	s_cbranch_vccnz .LBB0_556
	v_mov_b64_e32 v[36:37], s[20:21]
	v_mad_i64_i32 v[34:35], s[36:37], v34, s76, v[36:37]
	s_lshl_b32 s36, s13, 8
	s_ashr_i32 s37, s36, 31
	v_lshl_add_u64 v[34:35], s[36:37], 1, v[34:35]
	s_lshl_b32 s96, s67, 1
	v_lshl_add_u64 v[34:35], v[34:35], 0, s[96:97]
	v_lshl_add_u64 v[34:35], v[34:35], 0, v[162:163]
	v_pk_mul_f32 v[30:31], v[30:31], v[32:33] op_sel_hi:[1,0]
	v_pk_mul_f32 v[28:29], v[28:29], v[32:33] op_sel_hi:[1,0]
	v_pk_mul_f32 v[36:37], v[26:27], v[32:33] op_sel_hi:[1,0]
	v_pk_mul_f32 v[26:27], v[24:25], v[32:33] op_sel_hi:[1,0]
	v_cvt_pk_bf16_f32 v24, v28, v29
	v_cvt_pk_bf16_f32 v25, v30, v31
	v_pk_mul_f32 v[22:23], v[22:23], v[32:33] op_sel_hi:[1,0]
	v_cvt_pk_bf16_f32 v26, v26, v27
	v_cvt_pk_bf16_f32 v27, v36, v37
	global_store_dwordx4 v[34:35], v[24:27], off sc1
	v_pk_mul_f32 v[20:21], v[20:21], v[32:33] op_sel_hi:[1,0]
	s_nop 0
	v_pk_mul_f32 v[24:25], v[18:19], v[32:33] op_sel_hi:[1,0]
	v_pk_mul_f32 v[18:19], v[16:17], v[32:33] op_sel_hi:[1,0]
	v_cvt_pk_bf16_f32 v16, v20, v21
	v_cvt_pk_bf16_f32 v17, v22, v23
	s_nop 0
	v_cvt_pk_bf16_f32 v18, v18, v19
	v_cvt_pk_bf16_f32 v19, v24, v25
	global_store_dwordx4 v[34:35], v[16:19], off offset:256 sc1
.LBB0_556:
	s_nop 1
	v_add_u32_e32 v18, 0xb0, v142
	v_and_b32_e32 v16, 0xff, v18
	v_lshl_add_u32 v16, v16, 2, s58
	ds_read_b32 v16, v16
	s_and_b64 vcc, exec, s[46:47]
	s_mov_b64 s[36:37], -1
	s_waitcnt lgkmcnt(0)
	v_mul_f32_e32 v16, v145, v16
	s_cbranch_vccnz .LBB0_560
	s_and_saveexec_b64 s[36:37], s[42:43]
	s_cbranch_execz .LBB0_559
	v_ashrrev_i32_e32 v19, 31, v18
	v_lshlrev_b64 v[20:21], 5, v[18:19]
	v_lshl_add_u64 v[28:29], s[34:35], 0, v[20:21]
	v_pk_mul_f32 v[26:27], v[14:15], v[16:17] op_sel_hi:[1,0]
	v_pk_mul_f32 v[24:25], v[12:13], v[16:17] op_sel_hi:[1,0]
	v_pk_mul_f32 v[22:23], v[10:11], v[16:17] op_sel_hi:[1,0]
	v_pk_mul_f32 v[20:21], v[8:9], v[16:17] op_sel_hi:[1,0]
	global_store_dwordx4 v[28:29], v[24:27], off sc1
	global_store_dwordx4 v[28:29], v[20:23], off offset:16 sc1

.LBB0_560:
	s_andn2_b64 vcc, exec, s[36:37]
	s_cbranch_vccnz .LBB0_562
	v_mov_b64_e32 v[20:21], s[20:21]
	v_mad_i64_i32 v[18:19], s[36:37], v18, s76, v[20:21]
	s_lshl_b32 s36, s13, 8
	s_ashr_i32 s37, s36, 31
	v_lshl_add_u64 v[18:19], s[36:37], 1, v[18:19]
	s_lshl_b32 s96, s67, 1
	v_lshl_add_u64 v[18:19], v[18:19], 0, s[96:97]
	v_lshl_add_u64 v[18:19], v[18:19], 0, v[162:163]
	v_pk_mul_f32 v[14:15], v[14:15], v[16:17] op_sel_hi:[1,0]
	v_pk_mul_f32 v[12:13], v[12:13], v[16:17] op_sel_hi:[1,0]
	v_pk_mul_f32 v[20:21], v[10:11], v[16:17] op_sel_hi:[1,0]
	v_pk_mul_f32 v[10:11], v[8:9], v[16:17] op_sel_hi:[1,0]
	v_cvt_pk_bf16_f32 v8, v12, v13
	v_cvt_pk_bf16_f32 v9, v14, v15
	v_pk_mul_f32 v[6:7], v[6:7], v[16:17] op_sel_hi:[1,0]
	v_cvt_pk_bf16_f32 v10, v10, v11
	v_cvt_pk_bf16_f32 v11, v20, v21
	global_store_dwordx4 v[18:19], v[8:11], off sc1
	v_pk_mul_f32 v[4:5], v[4:5], v[16:17] op_sel_hi:[1,0]
	s_nop 0
	v_pk_mul_f32 v[8:9], v[2:3], v[16:17] op_sel_hi:[1,0]
	v_pk_mul_f32 v[2:3], v[0:1], v[16:17] op_sel_hi:[1,0]
	v_cvt_pk_bf16_f32 v0, v4, v5
	v_cvt_pk_bf16_f32 v1, v6, v7
	s_nop 0
	v_cvt_pk_bf16_f32 v2, v2, v3
	v_cvt_pk_bf16_f32 v3, v8, v9
	global_store_dwordx4 v[18:19], v[0:3], off offset:256 sc1
